# accumulator zero-init with 64-bit moves
# speedup vs baseline: 1.0025x; 1.0017x over previous
; #define PG8_STAGE(bufoff, gbase, voff) do { _Pragma("unroll") for (int _i = 0; _i < 2; ++_i) \
;         __builtin_amdgcn_global_load_lds((const unsigned*)((const char*)(gbase) + (voff)[_i]), (LAS unsigned*)(lds + (bufoff) + ldsw + _i * 8192), 16, 0, 0); } while (0)
; #define PG8_WAIT_V(n) asm volatile("s_waitcnt vmcnt(" #n ")" ::: "memory")
; #define PG8_BAR __builtin_amdgcn_s_barrier()
; template <class Epi, class Sched, bool ALIGN_EPI>
; __device__ __forceinline__ void gemm_phase(LAS unsigned char* lds, const bf16_t* Ab, const bf16_t* Bb, int lda, int ldb, int K, const Sched& S, Epi& E) {
;     ...
;     f32x4 acc[2][2][4][2];
; #pragma unroll
;     for (int a = 0; a < 2; ++a)
; #pragma unroll
;         for (int b = 0; b < 2; ++b)
; #pragma unroll
;             for (int m = 0; m < 4; ++m)
; #pragma unroll
;                 for (int n = 0; n < 2; ++n) acc[a][b][m][n] = (f32x4){0.f, 0.f, 0.f, 0.f};
;     bf16x8 At[4][2], B0[2][2], B1[2][2];
;     const char* cA = (const char*)(Ab + cur.a_off); const char* cB = (const char*)(Bb + cur.b_off);
;     PG8_STAGE(PG8_SB(0, 0), cB, voffB); PG8_STAGE(PG8_SB(0, 1), cB + hstepB, voffB); PG8_STAGE(PG8_SA(0, 0), cA, voffA); PG8_STAGE(PG8_SA(0, 1), cA + hstepA, voffA);
;     if (wr == 1) PG8_BAR;
;     PG8_WAIT_V(2); PG8_BAR;
;     PG8_STAGE(PG8_SB(1, 0), cB + kstep, voffB); PG8_STAGE(PG8_SA(1, 0), cA + kstep, voffA); PG8_STAGE(PG8_SB(1, 1), cB + hstepB + kstep, voffB);
;     PG8_WAIT_V(6); PG8_BAR;
.LBB0_522:
	s_add_u32 s12, s52, 0xe800000
	s_addc_u32 s13, s53, 0
	s_lshl_b32 s6, s6, 5
	s_and_b32 s6, s6, 0x60
	s_add_i32 m0, s44, 0x18000
	v_lshl_add_u64 v[10:11], v[10:11], 0, s[26:27]
	s_lshl_b32 s67, s7, 6
	s_lshl_b32 s68, s7, 13
	s_lshl_b32 s69, s6, 7
	s_waitcnt vmcnt(2)
	s_barrier
	global_load_lds_dwordx4 v[10:11], off
	v_lshl_add_u64 v[8:9], v[8:9], 0, s[26:27]
	s_add_i32 m0, s44, 0x1a000
	s_add_i32 s70, s44, 0x8000
	s_add_i32 s71, s44, 0xa000
	global_load_lds_dwordx4 v[8:9], off
	v_lshl_add_u64 v[2:3], v[2:3], 0, s[26:27]
	s_mov_b32 m0, s70
	s_add_u32 s8, s60, 0x40080
	global_load_lds_dwordx4 v[2:3], off
	v_lshl_add_u64 v[2:3], v[6:7], 0, s[26:27]
	s_mov_b32 m0, s71
	s_addc_u32 s9, s61, 0
	global_load_lds_dwordx4 v[2:3], off
	s_add_i32 m0, s44, 0x1c000
	v_lshl_add_u64 v[2:3], s[8:9], 0, v[0:1]
	global_load_lds_dwordx4 v[2:3], off
	v_lshl_add_u64 v[2:3], s[8:9], 0, v[132:133]
	s_add_i32 m0, s44, 0x1e000
	v_and_b32_e32 v5, 48, v98
	global_load_lds_dwordx4 v[2:3], off
	v_lshlrev_b32_e32 v12, 6, v98
	s_cmpk_lt_u32 s25, 0x100
	v_and_or_b32 v5, v12, s89, v5
	v_lshlrev_b32_e32 v12, 2, v98
	s_waitcnt vmcnt(6)
	s_cselect_b64 s[14:15], -1, 0
	s_lshl_b32 s7, s7, 8
	v_and_b32_e32 v12, 32, v12
	s_add_i32 s72, s7, 0
	v_mov_b32_e32 v2, 0
	v_bitop3_b32 v140, v5, s68, v12 bitop3:0xde
	v_bitop3_b32 v141, s69, v5, v12 bitop3:0xf6
	s_add_i32 s72, s72, 0x22100
	s_mov_b32 s75, 0
	s_lshl_b32 s18, s6, 1
	v_mov_b32_e32 v134, v0
	v_mov_b32_e32 v0, v4
	v_mov_b32_e32 v3, v2
	v_mov_b64_e32 v[4:5], 0
	v_mov_b64_e32 v[6:7], 0
	v_mov_b64_e32 v[8:9], 0
	v_mov_b64_e32 v[10:11], 0
	v_mov_b64_e32 v[12:13], 0
	s_waitcnt vmcnt(0)
	v_mov_b64_e32 v[14:15], 0
	v_mov_b64_e32 v[16:17], 0
	v_mov_b64_e32 v[18:19], 0
	v_mov_b64_e32 v[20:21], 0
	v_mov_b64_e32 v[22:23], 0
	v_mov_b64_e32 v[24:25], 0
	v_mov_b64_e32 v[26:27], 0
	v_mov_b64_e32 v[28:29], 0
	v_mov_b64_e32 v[30:31], 0
	v_mov_b64_e32 v[32:33], 0
	v_mov_b64_e32 v[34:35], 0
	v_mov_b64_e32 v[36:37], 0
	v_mov_b64_e32 v[38:39], 0
	v_mov_b64_e32 v[40:41], 0
	v_mov_b64_e32 v[42:43], 0
	v_mov_b64_e32 v[44:45], 0
	v_mov_b64_e32 v[46:47], 0
	v_mov_b64_e32 v[48:49], 0
	v_mov_b64_e32 v[50:51], 0
	v_mov_b64_e32 v[52:53], 0
	v_mov_b64_e32 v[54:55], 0
	v_mov_b64_e32 v[56:57], 0
	v_mov_b64_e32 v[58:59], 0
	v_mov_b64_e32 v[60:61], 0
	v_mov_b64_e32 v[62:63], 0
	v_mov_b64_e32 v[64:65], 0
	v_mov_b64_e32 v[66:67], 0
	v_mov_b64_e32 v[68:69], 0
	v_mov_b64_e32 v[70:71], 0
	v_mov_b64_e32 v[72:73], 0
	v_mov_b64_e32 v[74:75], 0
	v_mov_b64_e32 v[76:77], 0
	v_mov_b64_e32 v[78:79], 0
	v_mov_b64_e32 v[80:81], 0
	v_mov_b64_e32 v[82:83], 0
	v_mov_b64_e32 v[84:85], 0
	v_mov_b64_e32 v[86:87], 0
	v_mov_b64_e32 v[88:89], 0
	v_mov_b64_e32 v[90:91], 0
	v_mov_b64_e32 v[92:93], 0
	v_mov_b64_e32 v[94:95], 0
	v_mov_b64_e32 v[96:97], 0
	v_mov_b64_e32 v[98:99], 0
	v_mov_b64_e32 v[100:101], 0
	v_mov_b64_e32 v[102:103], 0
	v_mov_b64_e32 v[104:105], 0
	v_mov_b64_e32 v[106:107], 0
	v_mov_b64_e32 v[108:109], 0
	v_mov_b64_e32 v[110:111], 0
	v_mov_b64_e32 v[112:113], 0
	v_mov_b64_e32 v[114:115], 0
	v_mov_b64_e32 v[116:117], 0
	v_mov_b64_e32 v[118:119], 0
	v_mov_b64_e32 v[120:121], 0
	v_mov_b64_e32 v[122:123], 0
	v_mov_b64_e32 v[124:125], 0
	v_mov_b64_e32 v[126:127], 0
	v_mov_b64_e32 v[128:129], 0
	s_barrier
	s_branch .LBB0_524
; template <class Epi, class Sched, bool ALIGN_EPI>
; __device__ __forceinline__ void gemm_phase(LAS unsigned char* lds, const bf16_t* Ab, const bf16_t* Bb, int lda, int ldb, int K, const Sched& S, Epi& E) {
;     ...
; #pragma unroll
;         for (int a = 0; a < 2; ++a)
; #pragma unroll
;             for (int b = 0; b < 2; ++b)
; #pragma unroll
;                 for (int m = 0; m < 4; ++m)
; #pragma unroll
;                     for (int n = 0; n < 2; ++n) acc[a][b][m][n] = (f32x4){0.f, 0.f, 0.f, 0.f};
;         cur = nxt; cA = nA; cB = nB; ++ui;
;         { int t3 = threadIdx.x; asm volatile("" : "+v"(t3)); PG8_LANEOFFS(t3); }
.LBB0_523:
	v_bfe_i32 v4, v2, 27, 1
	v_lshlrev_b32_e32 v3, 4, v2
	v_lshrrev_b32_e32 v4, 22, v4
	v_add_u32_e32 v4, v3, v4
	v_and_b32_e32 v4, 0xfffffc00, v4
	v_sub_u32_e32 v4, v3, v4
	v_ashrrev_i32_e32 v0, 31, v2
	v_lshrrev_b32_e32 v5, 4, v4
	v_lshrrev_b32_e32 v0, 26, v0
	v_bitop3_b32 v4, v5, v4, 32 bitop3:0x6c
	v_add_u32_e32 v0, v2, v0
	v_ashrrev_i32_e32 v6, 31, v4
	v_ashrrev_i32_e32 v0, 6, v0
	v_lshrrev_b32_e32 v6, 26, v6
	v_lshlrev_b32_e32 v5, 3, v0
	v_add_u32_e32 v6, v4, v6
	v_and_b32_e32 v5, -16, v5
	v_ashrrev_i32_e32 v7, 6, v6
	v_and_b32_e32 v6, 0xc0, v6
	v_add_u32_e32 v5, v7, v5
	v_sub_u32_e32 v4, v4, v6
	v_lshlrev_b32_e32 v0, 5, v0
	v_ashrrev_i16_sdwa v4, v254, sext(v4) dst_sel:DWORD dst_unused:UNUSED_PAD src0_sel:DWORD src1_sel:BYTE_0
	v_lshlrev_b32_e32 v6, 1, v5
	v_lshrrev_b32_e32 v8, 2, v5
	v_and_b32_e32 v7, 3, v7
	v_and_b32_e32 v0, 32, v0
	v_bfe_i32 v4, v4, 0, 16
	v_and_b32_e32 v6, 24, v6
	v_and_b32_e32 v8, 4, v8
	v_and_or_b32 v7, v5, s86, v7
	v_or3_b32 v6, v7, v8, v6
	v_add_lshl_u32 v4, v0, v4, 1
	v_add_u32_e32 v3, 0x2000, v3
	v_lshl_add_u32 v0, v5, 11, v4
	v_lshl_add_u32 v134, v6, 11, v4
	v_ashrrev_i32_e32 v4, 31, v3
	v_lshrrev_b32_e32 v4, 22, v4
	v_add_u32_e32 v4, v3, v4
	v_ashrrev_i32_e32 v4, 10, v4
	v_mul_i32_i24_e32 v5, 0x400, v4
	v_sub_u32_e32 v3, v3, v5
	v_lshrrev_b32_e32 v5, 4, v3
	v_bitop3_b32 v3, v5, v3, 32 bitop3:0x6c
	v_ashrrev_i32_e32 v6, 31, v3
	v_lshrrev_b32_e32 v6, 26, v6
	v_lshlrev_b32_e32 v5, 3, v4
	v_add_u32_e32 v6, v3, v6
	v_and_b32_e32 v5, -16, v5
	v_ashrrev_i32_e32 v7, 6, v6
	v_and_b32_e32 v6, 0xc0, v6
	v_add_u32_e32 v5, v7, v5
	v_sub_u32_e32 v3, v3, v6
	v_lshlrev_b32_e32 v4, 5, v4
	v_ashrrev_i16_sdwa v3, v254, sext(v3) dst_sel:DWORD dst_unused:UNUSED_PAD src0_sel:DWORD src1_sel:BYTE_0
	v_lshlrev_b32_e32 v6, 1, v5
	v_lshrrev_b32_e32 v8, 2, v5
	v_and_b32_e32 v7, 3, v7
	v_and_b32_e32 v4, 32, v4
	v_bfe_i32 v3, v3, 0, 16
	v_and_b32_e32 v6, 24, v6
	v_and_b32_e32 v8, 4, v8
	v_and_or_b32 v7, v5, s86, v7
	v_or3_b32 v6, v7, v8, v6
	v_add_lshl_u32 v3, v4, v3, 1
	v_lshl_add_u32 v130, v5, 11, v3
	v_lshl_add_u32 v132, v6, 11, v3
	v_and_b32_e32 v3, 15, v2
	v_or_b32_e32 v4, s67, v3
	v_and_b32_e32 v5, 48, v2
	v_lshlrev_b32_e32 v2, 2, v2
	v_lshlrev_b32_e32 v6, 6, v4
	v_lshlrev_b32_e32 v4, 2, v4
	v_lshl_or_b32 v3, v3, 6, v5
	v_and_b32_e32 v2, 32, v2
	v_and_or_b32 v6, v6, s89, v5
	v_and_b32_e32 v4, 32, v4
	v_bitop3_b32 v141, v3, s69, v2 bitop3:0xde
	v_mov_b32_e32 v2, 0
	v_bitop3_b32 v140, v6, s68, v4 bitop3:0xde
	s_mov_b32 s4, s74
	s_mov_b32 s5, s73
	s_mov_b32 s75, s76
	v_mov_b32_e32 v3, v2
	v_mov_b64_e32 v[4:5], 0
	v_mov_b64_e32 v[6:7], 0
	v_mov_b64_e32 v[8:9], 0
	v_mov_b64_e32 v[10:11], 0
	v_mov_b64_e32 v[12:13], 0
	v_mov_b64_e32 v[14:15], 0
	v_mov_b64_e32 v[16:17], 0
	v_mov_b64_e32 v[18:19], 0
	v_mov_b64_e32 v[20:21], 0
	v_mov_b64_e32 v[22:23], 0
	v_mov_b64_e32 v[24:25], 0
	v_mov_b64_e32 v[26:27], 0
	v_mov_b64_e32 v[28:29], 0
	v_mov_b64_e32 v[30:31], 0
	v_mov_b64_e32 v[32:33], 0
	v_mov_b64_e32 v[34:35], 0
	v_mov_b64_e32 v[36:37], 0
	v_mov_b64_e32 v[38:39], 0
	v_mov_b64_e32 v[40:41], 0
	v_mov_b64_e32 v[42:43], 0
	v_mov_b64_e32 v[44:45], 0
	v_mov_b64_e32 v[46:47], 0
	v_mov_b64_e32 v[48:49], 0
	v_mov_b64_e32 v[50:51], 0
	v_mov_b64_e32 v[52:53], 0
	v_mov_b64_e32 v[54:55], 0
	v_mov_b64_e32 v[56:57], 0
	v_mov_b64_e32 v[58:59], 0
	v_mov_b64_e32 v[60:61], 0
	v_mov_b64_e32 v[62:63], 0
	v_mov_b64_e32 v[64:65], 0
	v_mov_b64_e32 v[66:67], 0
	v_mov_b64_e32 v[68:69], 0
	v_mov_b64_e32 v[70:71], 0
	v_mov_b64_e32 v[72:73], 0
	v_mov_b64_e32 v[74:75], 0
	v_mov_b64_e32 v[76:77], 0
	v_mov_b64_e32 v[78:79], 0
	v_mov_b64_e32 v[80:81], 0
	v_mov_b64_e32 v[82:83], 0
	v_mov_b64_e32 v[84:85], 0
	v_mov_b64_e32 v[86:87], 0
	v_mov_b64_e32 v[88:89], 0
	v_mov_b64_e32 v[90:91], 0
	v_mov_b64_e32 v[92:93], 0
	v_mov_b64_e32 v[94:95], 0
	v_mov_b64_e32 v[96:97], 0
	v_mov_b64_e32 v[98:99], 0
	v_mov_b64_e32 v[100:101], 0
	v_mov_b64_e32 v[102:103], 0
	v_mov_b64_e32 v[104:105], 0
	v_mov_b64_e32 v[106:107], 0
	v_mov_b64_e32 v[108:109], 0
	v_mov_b64_e32 v[110:111], 0
	v_mov_b64_e32 v[112:113], 0
	v_mov_b64_e32 v[114:115], 0
	v_mov_b64_e32 v[116:117], 0
	v_mov_b64_e32 v[118:119], 0
	v_mov_b64_e32 v[120:121], 0
	v_mov_b64_e32 v[122:123], 0
	v_mov_b64_e32 v[124:125], 0
	v_mov_b64_e32 v[126:127], 0
	v_mov_b64_e32 v[128:129], 0
	s_mov_b64 s[54:55], s[58:59]
	s_andn2_b64 vcc, exec, s[6:7]
	s_mov_b64 s[60:61], s[56:57]
	s_cbranch_vccz .LBB0_534

; template <class Epi, class Sched, bool ALIGN_EPI>
; __device__ __forceinline__ void gemm_phase(LAS unsigned char* lds, const bf16_t* Ab, const bf16_t* Bb, int lda, int ldb, int K, const Sched& S, Epi& E) {
;     ...
;         const bool has_next = S.next(ui + 1, nxt); nxt.ui = ui + 1;
;         const char* nA = has_next ? (const char*)(Ab + nxt.a_off) : cA; const char* nB = has_next ? (const char*)(Bb + nxt.b_off) : cB;
;         for (int t = 0; t < nt; t += 2) {
;             const bool last = (t == nt - 2);
;             const char* a1 = cA + (unsigned)(t + 1) * kstep;
;             const char* a2 = last ? nA : cA + (unsigned)(t + 2) * kstep; const char* b2 = last ? nB : cB + (unsigned)(t + 2) * kstep;
;             const char* a3 = a2 + kstep; const char* b3 = b2 + kstep;
;     ...
; #pragma unroll
;         for (int a = 0; a < 2; ++a)
; #pragma unroll
;             for (int b = 0; b < 2; ++b)
; #pragma unroll
;                 for (int m = 0; m < 4; ++m)
; #pragma unroll
;                     for (int n = 0; n < 2; ++n) acc[a][b][m][n] = (f32x4){0.f, 0.f, 0.f, 0.f};
.LBB0_606:
	s_mov_b32 s17, s19
	s_lshl_b64 s[54:55], s[16:17], 1
	s_add_u32 s54, s4, s54
	s_addc_u32 s55, s5, s55
	s_and_b64 s[56:57], s[6:7], exec
	s_mov_b32 s53, s19
	s_cselect_b32 s17, s55, s61
	s_cselect_b32 s18, s54, s60
	s_lshl_b64 s[56:57], s[52:53], 1
	s_add_u32 s56, s21, s56
	s_addc_u32 s57, s22, s57
	s_and_b64 s[62:63], s[6:7], exec
	s_cselect_b32 s25, s57, s59
	s_cselect_b32 s53, s56, s58
	s_add_u32 s77, s58, 0x100
	s_addc_u32 s78, s59, 0
	v_add_u32_e32 v3, s47, v2
	s_add_u32 s58, s60, 0xb0080
	v_mov_b32_e32 v2, 0
	v_add_u32_e32 v136, s64, v10
	v_mov_b32_e32 v133, v1
	v_mov_b32_e32 v131, v1
	v_mov_b32_e32 v135, v1
	s_addc_u32 s59, s61, 0
	s_mov_b32 s79, -2
	v_add_u32_e32 v137, 0, v3
	v_mov_b32_e32 v3, v2
	v_mov_b64_e32 v[4:5], 0
	v_mov_b64_e32 v[6:7], 0
	v_mov_b64_e32 v[8:9], 0
	v_mov_b64_e32 v[18:19], 0
	v_mov_b64_e32 v[20:21], 0
	v_mov_b64_e32 v[22:23], 0
	v_mov_b64_e32 v[24:25], 0
	v_mov_b64_e32 v[34:35], 0
	v_mov_b64_e32 v[36:37], 0
	v_mov_b64_e32 v[38:39], 0
	v_mov_b64_e32 v[40:41], 0
	v_mov_b64_e32 v[50:51], 0
	v_mov_b64_e32 v[52:53], 0
	v_mov_b64_e32 v[54:55], 0
	v_mov_b64_e32 v[56:57], 0
	v_mov_b64_e32 v[10:11], 0
	v_mov_b64_e32 v[12:13], 0
	v_mov_b64_e32 v[14:15], 0
	v_mov_b64_e32 v[16:17], 0
	v_mov_b64_e32 v[26:27], 0
	v_mov_b64_e32 v[28:29], 0
	v_mov_b64_e32 v[30:31], 0
	v_mov_b64_e32 v[32:33], 0
	v_mov_b64_e32 v[42:43], 0
	v_mov_b64_e32 v[44:45], 0
	v_mov_b64_e32 v[46:47], 0
	v_mov_b64_e32 v[48:49], 0
	v_mov_b64_e32 v[58:59], 0
	v_mov_b64_e32 v[60:61], 0
	v_mov_b64_e32 v[62:63], 0
	v_mov_b64_e32 v[64:65], 0
	v_mov_b64_e32 v[66:67], 0
	v_mov_b64_e32 v[68:69], 0
	v_mov_b64_e32 v[70:71], 0
	v_mov_b64_e32 v[72:73], 0
	v_mov_b64_e32 v[82:83], 0
	v_mov_b64_e32 v[84:85], 0
	v_mov_b64_e32 v[86:87], 0
	v_mov_b64_e32 v[88:89], 0
	v_mov_b64_e32 v[98:99], 0
	v_mov_b64_e32 v[100:101], 0
	v_mov_b64_e32 v[102:103], 0
	v_mov_b64_e32 v[104:105], 0
	v_mov_b64_e32 v[114:115], 0
	v_mov_b64_e32 v[116:117], 0
	v_mov_b64_e32 v[118:119], 0
	v_mov_b64_e32 v[120:121], 0
	v_mov_b64_e32 v[74:75], 0
	v_mov_b64_e32 v[76:77], 0
	v_mov_b64_e32 v[78:79], 0
	v_mov_b64_e32 v[80:81], 0
	v_mov_b64_e32 v[90:91], 0
	v_mov_b64_e32 v[92:93], 0
	v_mov_b64_e32 v[94:95], 0
	v_mov_b64_e32 v[96:97], 0
	v_mov_b64_e32 v[106:107], 0
	v_mov_b64_e32 v[108:109], 0
	v_mov_b64_e32 v[110:111], 0
	v_mov_b64_e32 v[112:113], 0
	v_mov_b64_e32 v[122:123], 0
	v_mov_b64_e32 v[124:125], 0
	v_mov_b64_e32 v[126:127], 0
	v_mov_b64_e32 v[128:129], 0

; #define PG8_STAGE(bufoff, gbase, voff) do { _Pragma("unroll") for (int _i = 0; _i < 2; ++_i) \
;         __builtin_amdgcn_global_load_lds((const unsigned*)((const char*)(gbase) + (voff)[_i]), (LAS unsigned*)(lds + (bufoff) + ldsw + _i * 8192), 16, 0, 0); } while (0)
; #define PG8_WAIT_V(n) asm volatile("s_waitcnt vmcnt(" #n ")" ::: "memory")
; #define PG8_BAR __builtin_amdgcn_s_barrier()
; template <class Epi, class Sched, bool ALIGN_EPI>
; __device__ __forceinline__ void gemm_phase(LAS unsigned char* lds, const bf16_t* Ab, const bf16_t* Bb, int lda, int ldb, int K, const Sched& S, Epi& E) {
;     ...
;     f32x4 acc[2][2][4][2];
; #pragma unroll
;     for (int a = 0; a < 2; ++a)
; #pragma unroll
;         for (int b = 0; b < 2; ++b)
; #pragma unroll
;             for (int m = 0; m < 4; ++m)
; #pragma unroll
;                 for (int n = 0; n < 2; ++n) acc[a][b][m][n] = (f32x4){0.f, 0.f, 0.f, 0.f};
;     bf16x8 At[4][2], B0[2][2], B1[2][2];
;     const char* cA = (const char*)(Ab + cur.a_off); const char* cB = (const char*)(Bb + cur.b_off);
;     PG8_STAGE(PG8_SB(0, 0), cB, voffB); PG8_STAGE(PG8_SB(0, 1), cB + hstepB, voffB); PG8_STAGE(PG8_SA(0, 0), cA, voffA); PG8_STAGE(PG8_SA(0, 1), cA + hstepA, voffA);
;     if (wr == 1) PG8_BAR;
;     PG8_WAIT_V(2); PG8_BAR;
;     PG8_STAGE(PG8_SB(1, 0), cB + kstep, voffB); PG8_STAGE(PG8_SA(1, 0), cA + kstep, voffA); PG8_STAGE(PG8_SB(1, 1), cB + hstepB + kstep, voffB);
;     PG8_WAIT_V(6); PG8_BAR;
.LBB0_740:
	s_add_u32 s54, s62, 0xe800000
	s_addc_u32 s55, s63, 0
	s_lshl_b32 s4, s4, 5
	s_and_b32 s4, s4, 0x60
	s_add_i32 m0, s47, 0x18000
	v_lshl_add_u64 v[10:11], v[10:11], 0, s[26:27]
	s_lshl_b32 s91, s6, 6
	s_lshl_b32 s92, s6, 13
	s_lshl_b32 s5, s4, 7
	s_waitcnt vmcnt(2)
	s_barrier
	global_load_lds_dwordx4 v[10:11], off
	v_lshl_add_u64 v[8:9], v[8:9], 0, s[26:27]
	s_add_i32 m0, s47, 0x1a000
	s_add_i32 s24, s47, 0x8000
	s_add_i32 s87, s47, 0xa000
	global_load_lds_dwordx4 v[8:9], off
	v_lshl_add_u64 v[2:3], v[2:3], 0, s[26:27]
	s_mov_b32 m0, s24
	s_add_u32 s8, s10, 0x40080
	global_load_lds_dwordx4 v[2:3], off
	v_lshl_add_u64 v[2:3], v[6:7], 0, s[26:27]
	s_mov_b32 m0, s87
	s_addc_u32 s9, s11, 0
	global_load_lds_dwordx4 v[2:3], off
	s_add_i32 m0, s47, 0x1c000
	v_lshl_add_u64 v[2:3], s[8:9], 0, v[0:1]
	global_load_lds_dwordx4 v[2:3], off
	v_lshl_add_u64 v[2:3], s[8:9], 0, v[132:133]
	s_add_i32 m0, s47, 0x1e000
	s_cmpk_lt_u32 s2, 0x100
	global_load_lds_dwordx4 v[2:3], off
	s_cselect_b64 s[56:57], -1, 0
	s_add_u32 s58, s62, 0x11000000
	s_addc_u32 s59, s63, 0
	s_add_u32 s60, s62, 0x13000000
	s_addc_u32 s61, s63, 0
	v_and_b32_e32 v5, 48, v98
	v_lshlrev_b32_e32 v12, 6, v98
	s_add_u32 s62, s62, 0x15000000
	v_and_or_b32 v5, v12, s89, v5
	v_lshlrev_b32_e32 v12, 2, v98
	s_waitcnt vmcnt(6)
	s_addc_u32 s63, s63, 0
	s_lshl_b32 s2, s6, 8
	v_and_b32_e32 v12, 32, v12
	s_add_i32 s2, s2, 0
	v_mov_b32_e32 v2, 0
	v_bitop3_b32 v160, v5, s92, v12 bitop3:0xde
	v_bitop3_b32 v161, s5, v5, v12 bitop3:0xf6
	s_add_i32 s2, s2, 0x22100
	s_mov_b32 s21, 0
	v_mov_b32_e32 v134, v0
	v_mov_b32_e32 v0, v4
	v_mov_b32_e32 v3, v2
	v_mov_b64_e32 v[4:5], 0
	v_mov_b64_e32 v[6:7], 0
	v_mov_b64_e32 v[8:9], 0
	v_mov_b64_e32 v[10:11], 0
	v_mov_b64_e32 v[12:13], 0
	s_waitcnt vmcnt(0)
	v_mov_b64_e32 v[14:15], 0
	v_mov_b64_e32 v[16:17], 0
	v_mov_b64_e32 v[18:19], 0
	v_mov_b64_e32 v[20:21], 0
	v_mov_b64_e32 v[22:23], 0
	v_mov_b64_e32 v[24:25], 0
	v_mov_b64_e32 v[26:27], 0
	v_mov_b64_e32 v[28:29], 0
	v_mov_b64_e32 v[30:31], 0
	v_mov_b64_e32 v[32:33], 0
	v_mov_b64_e32 v[34:35], 0
	v_mov_b64_e32 v[36:37], 0
	v_mov_b64_e32 v[38:39], 0
	v_mov_b64_e32 v[40:41], 0
	v_mov_b64_e32 v[42:43], 0
	v_mov_b64_e32 v[44:45], 0
	v_mov_b64_e32 v[46:47], 0
	v_mov_b64_e32 v[48:49], 0
	v_mov_b64_e32 v[50:51], 0
	v_mov_b64_e32 v[52:53], 0
	v_mov_b64_e32 v[54:55], 0
	v_mov_b64_e32 v[56:57], 0
	v_mov_b64_e32 v[58:59], 0
	v_mov_b64_e32 v[60:61], 0
	v_mov_b64_e32 v[62:63], 0
	v_mov_b64_e32 v[64:65], 0
	v_mov_b64_e32 v[66:67], 0
	v_mov_b64_e32 v[68:69], 0
	v_mov_b64_e32 v[70:71], 0
	v_mov_b64_e32 v[72:73], 0
	v_mov_b64_e32 v[74:75], 0
	v_mov_b64_e32 v[76:77], 0
	v_mov_b64_e32 v[78:79], 0
	v_mov_b64_e32 v[80:81], 0
	v_mov_b64_e32 v[82:83], 0
	v_mov_b64_e32 v[84:85], 0
	v_mov_b64_e32 v[86:87], 0
	v_mov_b64_e32 v[88:89], 0
	v_mov_b64_e32 v[90:91], 0
	v_mov_b64_e32 v[92:93], 0
	v_mov_b64_e32 v[94:95], 0
	v_mov_b64_e32 v[96:97], 0
	v_mov_b64_e32 v[98:99], 0
	v_mov_b64_e32 v[100:101], 0
	v_mov_b64_e32 v[102:103], 0
	v_mov_b64_e32 v[104:105], 0
	v_mov_b64_e32 v[106:107], 0
	v_mov_b64_e32 v[108:109], 0
	v_mov_b64_e32 v[110:111], 0
	v_mov_b64_e32 v[112:113], 0
	v_mov_b64_e32 v[114:115], 0
	v_mov_b64_e32 v[116:117], 0
	v_mov_b64_e32 v[118:119], 0
	v_mov_b64_e32 v[120:121], 0
	v_mov_b64_e32 v[122:123], 0
	v_mov_b64_e32 v[124:125], 0
	v_mov_b64_e32 v[126:127], 0
	v_mov_b64_e32 v[128:129], 0
	s_barrier
	s_branch .LBB0_742
; template <class Epi, class Sched, bool ALIGN_EPI>
; __device__ __forceinline__ void gemm_phase(LAS unsigned char* lds, const bf16_t* Ab, const bf16_t* Bb, int lda, int ldb, int K, const Sched& S, Epi& E) {
;     ...
; #pragma unroll
;         for (int a = 0; a < 2; ++a)
; #pragma unroll
;             for (int b = 0; b < 2; ++b)
; #pragma unroll
;                 for (int m = 0; m < 4; ++m)
; #pragma unroll
;                     for (int n = 0; n < 2; ++n) acc[a][b][m][n] = (f32x4){0.f, 0.f, 0.f, 0.f};
;         cur = nxt; cA = nA; cB = nB; ++ui;
;         { int t3 = threadIdx.x; asm volatile("" : "+v"(t3)); PG8_LANEOFFS(t3); }
.LBB0_741:
	v_bfe_i32 v4, v2, 27, 1
	v_lshlrev_b32_e32 v3, 4, v2
	v_lshrrev_b32_e32 v4, 22, v4
	v_add_u32_e32 v4, v3, v4
	v_and_b32_e32 v4, 0xfffffc00, v4
	v_sub_u32_e32 v4, v3, v4
	v_ashrrev_i32_e32 v0, 31, v2
	v_lshrrev_b32_e32 v5, 4, v4
	v_lshrrev_b32_e32 v0, 26, v0
	v_bitop3_b32 v4, v5, v4, 32 bitop3:0x6c
	v_add_u32_e32 v0, v2, v0
	v_ashrrev_i32_e32 v6, 31, v4
	v_ashrrev_i32_e32 v0, 6, v0
	v_lshrrev_b32_e32 v6, 26, v6
	v_lshlrev_b32_e32 v5, 3, v0
	v_add_u32_e32 v6, v4, v6
	v_and_b32_e32 v5, -16, v5
	v_ashrrev_i32_e32 v7, 6, v6
	v_and_b32_e32 v6, 0xc0, v6
	v_add_u32_e32 v5, v7, v5
	v_sub_u32_e32 v4, v4, v6
	v_lshlrev_b32_e32 v0, 5, v0
	v_ashrrev_i16_sdwa v4, v254, sext(v4) dst_sel:DWORD dst_unused:UNUSED_PAD src0_sel:DWORD src1_sel:BYTE_0
	v_lshlrev_b32_e32 v6, 1, v5
	v_lshrrev_b32_e32 v8, 2, v5
	v_and_b32_e32 v7, 3, v7
	v_and_b32_e32 v0, 32, v0
	v_bfe_i32 v4, v4, 0, 16
	v_and_b32_e32 v6, 24, v6
	v_and_b32_e32 v8, 4, v8
	v_and_or_b32 v7, v5, s86, v7
	v_or3_b32 v6, v7, v8, v6
	v_add_lshl_u32 v4, v0, v4, 1
	v_add_u32_e32 v3, 0x2000, v3
	v_lshl_add_u32 v0, v5, 11, v4
	v_lshl_add_u32 v134, v6, 11, v4
	v_ashrrev_i32_e32 v4, 31, v3
	v_lshrrev_b32_e32 v4, 22, v4
	v_add_u32_e32 v4, v3, v4
	v_ashrrev_i32_e32 v4, 10, v4
	v_mul_i32_i24_e32 v5, 0x400, v4
	v_sub_u32_e32 v3, v3, v5
	v_lshrrev_b32_e32 v5, 4, v3
	v_bitop3_b32 v3, v5, v3, 32 bitop3:0x6c
	v_ashrrev_i32_e32 v6, 31, v3
	v_lshrrev_b32_e32 v6, 26, v6
	v_lshlrev_b32_e32 v5, 3, v4
	v_add_u32_e32 v6, v3, v6
	v_and_b32_e32 v5, -16, v5
	v_ashrrev_i32_e32 v7, 6, v6
	v_and_b32_e32 v6, 0xc0, v6
	v_add_u32_e32 v5, v7, v5
	v_sub_u32_e32 v3, v3, v6
	v_lshlrev_b32_e32 v4, 5, v4
	v_ashrrev_i16_sdwa v3, v254, sext(v3) dst_sel:DWORD dst_unused:UNUSED_PAD src0_sel:DWORD src1_sel:BYTE_0
	v_lshlrev_b32_e32 v6, 1, v5
	v_lshrrev_b32_e32 v8, 2, v5
	v_and_b32_e32 v7, 3, v7
	v_and_b32_e32 v4, 32, v4
	v_bfe_i32 v3, v3, 0, 16
	v_and_b32_e32 v6, 24, v6
	v_and_b32_e32 v8, 4, v8
	v_and_or_b32 v7, v5, s86, v7
	v_or3_b32 v6, v7, v8, v6
	v_add_lshl_u32 v3, v4, v3, 1
	v_lshl_add_u32 v130, v5, 11, v3
	v_lshl_add_u32 v132, v6, 11, v3
	v_and_b32_e32 v3, 15, v2
	v_or_b32_e32 v4, s91, v3
	v_and_b32_e32 v5, 48, v2
	v_lshlrev_b32_e32 v2, 2, v2
	v_lshlrev_b32_e32 v6, 6, v4
	v_lshlrev_b32_e32 v4, 2, v4
	v_lshl_or_b32 v3, v3, 6, v5
	v_and_b32_e32 v2, 32, v2
	v_and_or_b32 v6, v6, s89, v5
	v_and_b32_e32 v4, 32, v4
	v_bitop3_b32 v161, v3, s5, v2 bitop3:0xde
	v_mov_b32_e32 v2, 0
	v_bitop3_b32 v160, v6, s92, v4 bitop3:0xde
	s_mov_b32 s94, s78
	s_mov_b32 s79, s88
	s_mov_b32 s21, s95
	v_mov_b32_e32 v3, v2
	v_mov_b64_e32 v[4:5], 0
	v_mov_b64_e32 v[6:7], 0
	v_mov_b64_e32 v[8:9], 0
	v_mov_b64_e32 v[10:11], 0
	v_mov_b64_e32 v[12:13], 0
	v_mov_b64_e32 v[14:15], 0
	v_mov_b64_e32 v[16:17], 0
	v_mov_b64_e32 v[18:19], 0
	v_mov_b64_e32 v[20:21], 0
	v_mov_b64_e32 v[22:23], 0
	v_mov_b64_e32 v[24:25], 0
	v_mov_b64_e32 v[26:27], 0
	v_mov_b64_e32 v[28:29], 0
	v_mov_b64_e32 v[30:31], 0
	v_mov_b64_e32 v[32:33], 0
	v_mov_b64_e32 v[34:35], 0
	v_mov_b64_e32 v[36:37], 0
	v_mov_b64_e32 v[38:39], 0
	v_mov_b64_e32 v[40:41], 0
	v_mov_b64_e32 v[42:43], 0
	v_mov_b64_e32 v[44:45], 0
	v_mov_b64_e32 v[46:47], 0
	v_mov_b64_e32 v[48:49], 0
	v_mov_b64_e32 v[50:51], 0
	v_mov_b64_e32 v[52:53], 0
	v_mov_b64_e32 v[54:55], 0
	v_mov_b64_e32 v[56:57], 0
	v_mov_b64_e32 v[58:59], 0
	v_mov_b64_e32 v[60:61], 0
	v_mov_b64_e32 v[62:63], 0
	v_mov_b64_e32 v[64:65], 0
	v_mov_b64_e32 v[66:67], 0
	v_mov_b64_e32 v[68:69], 0
	v_mov_b64_e32 v[70:71], 0
	v_mov_b64_e32 v[72:73], 0
	v_mov_b64_e32 v[74:75], 0
	v_mov_b64_e32 v[76:77], 0
	v_mov_b64_e32 v[78:79], 0
	v_mov_b64_e32 v[80:81], 0
	v_mov_b64_e32 v[82:83], 0
	v_mov_b64_e32 v[84:85], 0
	v_mov_b64_e32 v[86:87], 0
	v_mov_b64_e32 v[88:89], 0
	v_mov_b64_e32 v[90:91], 0
	v_mov_b64_e32 v[92:93], 0
	v_mov_b64_e32 v[94:95], 0
	v_mov_b64_e32 v[96:97], 0
	v_mov_b64_e32 v[98:99], 0
	v_mov_b64_e32 v[100:101], 0
	v_mov_b64_e32 v[102:103], 0
	v_mov_b64_e32 v[104:105], 0
	v_mov_b64_e32 v[106:107], 0
	v_mov_b64_e32 v[108:109], 0
	v_mov_b64_e32 v[110:111], 0
	v_mov_b64_e32 v[112:113], 0
	v_mov_b64_e32 v[114:115], 0
	v_mov_b64_e32 v[116:117], 0
	v_mov_b64_e32 v[118:119], 0
	v_mov_b64_e32 v[120:121], 0
	v_mov_b64_e32 v[122:123], 0
	v_mov_b64_e32 v[124:125], 0
	v_mov_b64_e32 v[126:127], 0
	v_mov_b64_e32 v[128:129], 0
	s_mov_b64 s[66:67], s[70:71]
	s_andn2_b64 vcc, exec, s[6:7]
	s_mov_b64 s[10:11], s[68:69]
	s_cbranch_vccz .LBB0_948

; template <class Epi, class Sched, bool ALIGN_EPI>
; __device__ __forceinline__ void gemm_phase(LAS unsigned char* lds, const bf16_t* Ab, const bf16_t* Bb, int lda, int ldb, int K, const Sched& S, Epi& E) {
;     ...
;         const bool has_next = S.next(ui + 1, nxt); nxt.ui = ui + 1;
;         const char* nA = has_next ? (const char*)(Ab + nxt.a_off) : cA; const char* nB = has_next ? (const char*)(Bb + nxt.b_off) : cB;
;         for (int t = 0; t < nt; t += 2) {
;             const bool last = (t == nt - 2);
;             const char* a1 = cA + (unsigned)(t + 1) * kstep;
;             const char* a2 = last ? nA : cA + (unsigned)(t + 2) * kstep; const char* b2 = last ? nB : cB + (unsigned)(t + 2) * kstep;
;             const char* a3 = a2 + kstep; const char* b3 = b2 + kstep;
;     ...
; #pragma unroll
;         for (int a = 0; a < 2; ++a)
; #pragma unroll
;             for (int b = 0; b < 2; ++b)
; #pragma unroll
;                 for (int m = 0; m < 4; ++m)
; #pragma unroll
;                     for (int n = 0; n < 2; ++n) acc[a][b][m][n] = (f32x4){0.f, 0.f, 0.f, 0.f};
.LBB0_1016:
	s_lshl_b64 s[12:13], s[18:19], 1
	s_add_u32 s12, s4, s12
	s_addc_u32 s13, s5, s13
	s_and_b64 s[14:15], s[16:17], exec
	s_mov_b32 s11, s19
	s_cselect_b32 s7, s13, s51
	s_cselect_b32 s69, s12, s50
	s_lshl_b64 s[14:15], s[10:11], 1
	s_add_u32 s14, s21, s14
	s_addc_u32 s15, s22, s15
	s_and_b64 s[54:55], s[16:17], exec
	s_cselect_b32 s11, s15, s53
	s_cselect_b32 s70, s14, s52
	s_add_u32 s50, s50, 0x40080
	s_addc_u32 s51, s51, 0
	v_add_u32_e32 v3, s57, v10
	s_add_u32 s71, s52, 0x100
	v_mov_b32_e32 v2, 0
	v_mov_b32_e32 v135, v1
	v_mov_b32_e32 v131, v1
	v_mov_b32_e32 v133, v1
	s_addc_u32 s72, s53, 0
	s_mov_b32 s73, -2
	v_add_u32_e32 v137, 0, v3
	v_mov_b32_e32 v3, v2
	v_mov_b64_e32 v[4:5], 0
	v_mov_b64_e32 v[6:7], 0
	v_mov_b64_e32 v[8:9], 0
	v_mov_b64_e32 v[18:19], 0
	v_mov_b64_e32 v[20:21], 0
	v_mov_b64_e32 v[22:23], 0
	v_mov_b64_e32 v[24:25], 0
	v_mov_b64_e32 v[34:35], 0
	v_mov_b64_e32 v[36:37], 0
	v_mov_b64_e32 v[38:39], 0
	v_mov_b64_e32 v[40:41], 0
	v_mov_b64_e32 v[50:51], 0
	v_mov_b64_e32 v[52:53], 0
	v_mov_b64_e32 v[54:55], 0
	v_mov_b64_e32 v[56:57], 0
	v_mov_b64_e32 v[10:11], 0
	v_mov_b64_e32 v[12:13], 0
	v_mov_b64_e32 v[14:15], 0
	v_mov_b64_e32 v[16:17], 0
	v_mov_b64_e32 v[26:27], 0
	v_mov_b64_e32 v[28:29], 0
	v_mov_b64_e32 v[30:31], 0
	v_mov_b64_e32 v[32:33], 0
	v_mov_b64_e32 v[42:43], 0
	v_mov_b64_e32 v[44:45], 0
	v_mov_b64_e32 v[46:47], 0
	v_mov_b64_e32 v[48:49], 0
	v_mov_b64_e32 v[58:59], 0
	v_mov_b64_e32 v[60:61], 0
	v_mov_b64_e32 v[62:63], 0
	v_mov_b64_e32 v[64:65], 0
	v_mov_b64_e32 v[66:67], 0
	v_mov_b64_e32 v[68:69], 0
	v_mov_b64_e32 v[70:71], 0
	v_mov_b64_e32 v[72:73], 0
	v_mov_b64_e32 v[82:83], 0
	v_mov_b64_e32 v[84:85], 0
	v_mov_b64_e32 v[86:87], 0
	v_mov_b64_e32 v[88:89], 0
	v_mov_b64_e32 v[98:99], 0
	v_mov_b64_e32 v[100:101], 0
	v_mov_b64_e32 v[102:103], 0
	v_mov_b64_e32 v[104:105], 0
	v_mov_b64_e32 v[114:115], 0
	v_mov_b64_e32 v[116:117], 0
	v_mov_b64_e32 v[118:119], 0
	v_mov_b64_e32 v[120:121], 0
	v_mov_b64_e32 v[74:75], 0
	v_mov_b64_e32 v[76:77], 0
	v_mov_b64_e32 v[78:79], 0
	v_mov_b64_e32 v[80:81], 0
	v_mov_b64_e32 v[90:91], 0
	v_mov_b64_e32 v[92:93], 0
	v_mov_b64_e32 v[94:95], 0
	v_mov_b64_e32 v[96:97], 0
	v_mov_b64_e32 v[106:107], 0
	v_mov_b64_e32 v[108:109], 0
	v_mov_b64_e32 v[110:111], 0
	v_mov_b64_e32 v[112:113], 0
	v_mov_b64_e32 v[122:123], 0
	v_mov_b64_e32 v[124:125], 0
	v_mov_b64_e32 v[126:127], 0
	v_mov_b64_e32 v[128:129], 0

; template <class Epi, class Sched, bool ALIGN_EPI>
; __device__ __forceinline__ void gemm_phase(LAS unsigned char* lds, const bf16_t* Ab, const bf16_t* Bb, int lda, int ldb, int K, const Sched& S, Epi& E) {
;     ...
;         const bool has_next = S.next(ui + 1, nxt); nxt.ui = ui + 1;
;         const char* nA = has_next ? (const char*)(Ab + nxt.a_off) : cA; const char* nB = has_next ? (const char*)(Bb + nxt.b_off) : cB;
;         for (int t = 0; t < nt; t += 2) {
;             const bool last = (t == nt - 2);
;             const char* a1 = cA + (unsigned)(t + 1) * kstep;
;             const char* a2 = last ? nA : cA + (unsigned)(t + 2) * kstep; const char* b2 = last ? nB : cB + (unsigned)(t + 2) * kstep;
;             const char* a3 = a2 + kstep; const char* b3 = b2 + kstep;
;     ...
; #pragma unroll
;         for (int a = 0; a < 2; ++a)
; #pragma unroll
;             for (int b = 0; b < 2; ++b)
; #pragma unroll
;                 for (int m = 0; m < 4; ++m)
; #pragma unroll
;                     for (int n = 0; n < 2; ++n) acc[a][b][m][n] = (f32x4){0.f, 0.f, 0.f, 0.f};
.LBB0_1175:
	s_lshl_b64 s[10:11], s[18:19], 1
	s_add_u32 s10, s21, s10
	s_addc_u32 s11, s22, s11
	s_and_b64 s[12:13], s[14:15], exec
	s_mov_b32 s9, s19
	s_cselect_b32 s64, s11, s17
	s_cselect_b32 s65, s10, s16
	s_lshl_b64 s[12:13], s[8:9], 1
	s_add_u32 s12, s24, s12
	s_addc_u32 s13, s33, s13
	s_and_b64 s[52:53], s[14:15], exec
	s_cselect_b32 s9, s13, s51
	s_cselect_b32 s66, s12, s50
	s_add_u32 s16, s16, 0x28080
	s_addc_u32 s17, s17, 0
	v_add_u32_e32 v3, s55, v2
	s_add_u32 s67, s50, 0x100
	v_mov_b32_e32 v2, 0
	v_mov_b32_e32 v133, v1
	v_mov_b32_e32 v131, v1
	v_mov_b32_e32 v135, v1
	s_addc_u32 s68, s51, 0
	s_mov_b32 s69, -2
	v_add_u32_e32 v137, 0, v3
	v_mov_b32_e32 v3, v2
	v_mov_b64_e32 v[4:5], 0
	v_mov_b64_e32 v[6:7], 0
	v_mov_b64_e32 v[8:9], 0
	v_mov_b64_e32 v[18:19], 0
	v_mov_b64_e32 v[20:21], 0
	v_mov_b64_e32 v[22:23], 0
	v_mov_b64_e32 v[24:25], 0
	v_mov_b64_e32 v[34:35], 0
	v_mov_b64_e32 v[36:37], 0
	v_mov_b64_e32 v[38:39], 0
	v_mov_b64_e32 v[40:41], 0
	v_mov_b64_e32 v[50:51], 0
	v_mov_b64_e32 v[52:53], 0
	v_mov_b64_e32 v[54:55], 0
	v_mov_b64_e32 v[56:57], 0
	v_mov_b64_e32 v[10:11], 0
	v_mov_b64_e32 v[12:13], 0
	v_mov_b64_e32 v[14:15], 0
	v_mov_b64_e32 v[16:17], 0
	v_mov_b64_e32 v[26:27], 0
	v_mov_b64_e32 v[28:29], 0
	v_mov_b64_e32 v[30:31], 0
	v_mov_b64_e32 v[32:33], 0
	v_mov_b64_e32 v[42:43], 0
	v_mov_b64_e32 v[44:45], 0
	v_mov_b64_e32 v[46:47], 0
	v_mov_b64_e32 v[48:49], 0
	v_mov_b64_e32 v[58:59], 0
	v_mov_b64_e32 v[60:61], 0
	v_mov_b64_e32 v[62:63], 0
	v_mov_b64_e32 v[64:65], 0
	v_mov_b64_e32 v[66:67], 0
	v_mov_b64_e32 v[68:69], 0
	v_mov_b64_e32 v[70:71], 0
	v_mov_b64_e32 v[72:73], 0
	v_mov_b64_e32 v[82:83], 0
	v_mov_b64_e32 v[84:85], 0
	v_mov_b64_e32 v[86:87], 0
	v_mov_b64_e32 v[88:89], 0
	v_mov_b64_e32 v[98:99], 0
	v_mov_b64_e32 v[100:101], 0
	v_mov_b64_e32 v[102:103], 0
	v_mov_b64_e32 v[104:105], 0
	v_mov_b64_e32 v[114:115], 0
	v_mov_b64_e32 v[116:117], 0
	v_mov_b64_e32 v[118:119], 0
	v_mov_b64_e32 v[120:121], 0
	v_mov_b64_e32 v[74:75], 0
	v_mov_b64_e32 v[76:77], 0
	v_mov_b64_e32 v[78:79], 0
	v_mov_b64_e32 v[80:81], 0
	v_mov_b64_e32 v[90:91], 0
	v_mov_b64_e32 v[92:93], 0
	v_mov_b64_e32 v[94:95], 0
	v_mov_b64_e32 v[96:97], 0
	v_mov_b64_e32 v[106:107], 0
	v_mov_b64_e32 v[108:109], 0
	v_mov_b64_e32 v[110:111], 0
	v_mov_b64_e32 v[112:113], 0
	v_mov_b64_e32 v[122:123], 0
	v_mov_b64_e32 v[124:125], 0
	v_mov_b64_e32 v[126:127], 0
	v_mov_b64_e32 v[128:129], 0

; #define PG8_STAGE(bufoff, gbase, voff) do { _Pragma("unroll") for (int _i = 0; _i < 2; ++_i) \
;         __builtin_amdgcn_global_load_lds((const unsigned*)((const char*)(gbase) + (voff)[_i]), (LAS unsigned*)(lds + (bufoff) + ldsw + _i * 8192), 16, 0, 0); } while (0)
; #define PG8_WAIT_V(n) asm volatile("s_waitcnt vmcnt(" #n ")" ::: "memory")
; #define PG8_BAR __builtin_amdgcn_s_barrier()
; template <class Epi, class Sched, bool ALIGN_EPI>
; __device__ __forceinline__ void gemm_phase(LAS unsigned char* lds, const bf16_t* Ab, const bf16_t* Bb, int lda, int ldb, int K, const Sched& S, Epi& E) {
;     ...
;     f32x4 acc[2][2][4][2];
; #pragma unroll
;     for (int a = 0; a < 2; ++a)
; #pragma unroll
;         for (int b = 0; b < 2; ++b)
; #pragma unroll
;             for (int m = 0; m < 4; ++m)
; #pragma unroll
;                 for (int n = 0; n < 2; ++n) acc[a][b][m][n] = (f32x4){0.f, 0.f, 0.f, 0.f};
;     bf16x8 At[4][2], B0[2][2], B1[2][2];
;     const char* cA = (const char*)(Ab + cur.a_off); const char* cB = (const char*)(Bb + cur.b_off);
;     PG8_STAGE(PG8_SB(0, 0), cB, voffB); PG8_STAGE(PG8_SB(0, 1), cB + hstepB, voffB); PG8_STAGE(PG8_SA(0, 0), cA, voffA); PG8_STAGE(PG8_SA(0, 1), cA + hstepA, voffA);
;     if (wr == 1) PG8_BAR;
;     PG8_WAIT_V(2); PG8_BAR;
;     PG8_STAGE(PG8_SB(1, 0), cB + kstep, voffB); PG8_STAGE(PG8_SA(1, 0), cA + kstep, voffA); PG8_STAGE(PG8_SB(1, 1), cB + hstepB + kstep, voffB);
;     PG8_WAIT_V(6); PG8_BAR;
.LBB0_1492:
	v_readlane_b32 s8, v255, 13
	s_add_u32 s12, s52, 0xa800000
	v_readlane_b32 s9, v255, 14
	s_addc_u32 s13, s53, 0
	s_lshl_b64 s[8:9], s[8:9], 2
	s_add_u32 s8, s52, s8
	s_addc_u32 s9, s53, s9
	s_add_u32 s14, s8, 0x1d600000
	s_addc_u32 s15, s9, 0
	s_and_b32 s68, s7, 3
	s_add_i32 m0, s44, 0x18000
	v_lshl_add_u64 v[8:9], v[8:9], 0, s[26:27]
	s_lshl_b32 s69, s6, 6
	s_lshl_b32 s70, s6, 13
	s_lshl_b32 s71, s68, 5
	s_lshl_b32 s72, s68, 12
	s_waitcnt vmcnt(2)
	s_barrier
	global_load_lds_dwordx4 v[8:9], off
	v_lshl_add_u64 v[6:7], v[6:7], 0, s[26:27]
	s_add_i32 m0, s44, 0x1a000
	s_add_i32 s73, s44, 0x8000
	s_add_i32 s74, s44, 0xa000
	global_load_lds_dwordx4 v[6:7], off
	v_lshl_add_u64 v[2:3], v[2:3], 0, s[26:27]
	s_mov_b32 m0, s73
	s_add_u32 s8, s62, 0x40080
	global_load_lds_dwordx4 v[2:3], off
	v_lshl_add_u64 v[2:3], v[4:5], 0, s[26:27]
	s_mov_b32 m0, s74
	s_addc_u32 s9, s63, 0
	global_load_lds_dwordx4 v[2:3], off
	s_add_i32 m0, s44, 0x1c000
	v_lshl_add_u64 v[2:3], s[8:9], 0, v[0:1]
	global_load_lds_dwordx4 v[2:3], off
	v_lshl_add_u64 v[2:3], s[8:9], 0, v[158:159]
	s_add_i32 m0, s44, 0x1e000
	s_cmpk_lt_u32 s31, 0x100
	global_load_lds_dwordx4 v[2:3], off
	s_cselect_b64 s[16:17], -1, 0
	s_lshl_b32 s7, s68, 6
	v_and_b32_e32 v10, 48, v98
	v_lshlrev_b32_e32 v11, 6, v98
	s_add_u32 s75, s12, s7
	v_and_or_b32 v10, v11, s89, v10
	v_lshlrev_b32_e32 v11, 2, v98
	s_waitcnt vmcnt(6)
	s_addc_u32 s76, s13, 0
	s_lshl_b32 s6, s6, 8
	v_and_b32_e32 v11, 32, v11
	s_add_i32 s77, s6, 0
	v_mov_b32_e32 v2, 0
	v_bitop3_b32 v178, v10, s70, v11 bitop3:0xde
	v_bitop3_b32 v179, v10, s72, v11 bitop3:0xde
	s_add_i32 s77, s77, 0x22100
	s_mov_b32 s80, 0
	v_mov_b32_e32 v160, v0
	v_mov_b32_e32 v3, v2
	v_mov_b64_e32 v[4:5], 0
	v_mov_b64_e32 v[6:7], 0
	v_mov_b64_e32 v[8:9], 0
	v_mov_b64_e32 v[10:11], 0
	v_mov_b64_e32 v[12:13], 0
	s_waitcnt vmcnt(0)
	v_mov_b64_e32 v[14:15], 0
	v_mov_b64_e32 v[16:17], 0
	v_mov_b64_e32 v[18:19], 0
	v_mov_b64_e32 v[20:21], 0
	v_mov_b64_e32 v[22:23], 0
	v_mov_b64_e32 v[24:25], 0
	v_mov_b64_e32 v[26:27], 0
	v_mov_b64_e32 v[28:29], 0
	v_mov_b64_e32 v[30:31], 0
	v_mov_b64_e32 v[32:33], 0
	v_mov_b64_e32 v[34:35], 0
	v_mov_b64_e32 v[36:37], 0
	v_mov_b64_e32 v[38:39], 0
	v_mov_b64_e32 v[40:41], 0
	v_mov_b64_e32 v[42:43], 0
	v_mov_b64_e32 v[44:45], 0
	v_mov_b64_e32 v[46:47], 0
	v_mov_b64_e32 v[48:49], 0
	v_mov_b64_e32 v[50:51], 0
	v_mov_b64_e32 v[52:53], 0
	v_mov_b64_e32 v[54:55], 0
	v_mov_b64_e32 v[56:57], 0
	v_mov_b64_e32 v[58:59], 0
	v_mov_b64_e32 v[60:61], 0
	v_mov_b64_e32 v[62:63], 0
	v_mov_b64_e32 v[64:65], 0
	v_mov_b64_e32 v[66:67], 0
	v_mov_b64_e32 v[68:69], 0
	v_mov_b64_e32 v[70:71], 0
	v_mov_b64_e32 v[72:73], 0
	v_mov_b64_e32 v[74:75], 0
	v_mov_b64_e32 v[76:77], 0
	v_mov_b64_e32 v[78:79], 0
	v_mov_b64_e32 v[80:81], 0
	v_mov_b64_e32 v[82:83], 0
	v_mov_b64_e32 v[84:85], 0
	v_mov_b64_e32 v[86:87], 0
	v_mov_b64_e32 v[88:89], 0
	v_mov_b64_e32 v[90:91], 0
	v_mov_b64_e32 v[92:93], 0
	v_mov_b64_e32 v[94:95], 0
	v_mov_b64_e32 v[96:97], 0
	v_mov_b64_e32 v[98:99], 0
	v_mov_b64_e32 v[100:101], 0
	v_mov_b64_e32 v[102:103], 0
	v_mov_b64_e32 v[104:105], 0
	v_mov_b64_e32 v[106:107], 0
	v_mov_b64_e32 v[108:109], 0
	v_mov_b64_e32 v[110:111], 0
	v_mov_b64_e32 v[112:113], 0
	v_mov_b64_e32 v[114:115], 0
	v_mov_b64_e32 v[116:117], 0
	v_mov_b64_e32 v[118:119], 0
	v_mov_b64_e32 v[120:121], 0
	v_mov_b64_e32 v[122:123], 0
	v_mov_b64_e32 v[124:125], 0
	v_mov_b64_e32 v[126:127], 0
	v_mov_b64_e32 v[128:129], 0
	s_barrier
	s_branch .LBB0_1494
; template <class Epi, class Sched, bool ALIGN_EPI>
; __device__ __forceinline__ void gemm_phase(LAS unsigned char* lds, const bf16_t* Ab, const bf16_t* Bb, int lda, int ldb, int K, const Sched& S, Epi& E) {
;     ...
; #pragma unroll
;         for (int a = 0; a < 2; ++a)
; #pragma unroll
;             for (int b = 0; b < 2; ++b)
; #pragma unroll
;                 for (int m = 0; m < 4; ++m)
; #pragma unroll
;                     for (int n = 0; n < 2; ++n) acc[a][b][m][n] = (f32x4){0.f, 0.f, 0.f, 0.f};
;         cur = nxt; cA = nA; cB = nB; ++ui;
;         { int t3 = threadIdx.x; asm volatile("" : "+v"(t3)); PG8_LANEOFFS(t3); }
.LBB0_1493:
	v_bfe_i32 v4, v0, 27, 1
	v_lshlrev_b32_e32 v2, 4, v0
	v_lshrrev_b32_e32 v4, 22, v4
	v_add_u32_e32 v4, v2, v4
	v_and_b32_e32 v4, 0xfffffc00, v4
	v_sub_u32_e32 v4, v2, v4
	v_ashrrev_i32_e32 v3, 31, v0
	v_lshrrev_b32_e32 v5, 4, v4
	v_lshrrev_b32_e32 v3, 26, v3
	v_bitop3_b32 v4, v5, v4, 32 bitop3:0x6c
	v_add_u32_e32 v3, v0, v3
	v_ashrrev_i32_e32 v6, 31, v4
	v_ashrrev_i32_e32 v3, 6, v3
	v_lshrrev_b32_e32 v6, 26, v6
	v_lshlrev_b32_e32 v5, 3, v3
	v_add_u32_e32 v6, v4, v6
	v_and_b32_e32 v5, -16, v5
	v_ashrrev_i32_e32 v7, 6, v6
	v_and_b32_e32 v6, 0xc0, v6
	v_add_u32_e32 v5, v7, v5
	v_sub_u32_e32 v4, v4, v6
	v_lshlrev_b32_e32 v3, 5, v3
	v_ashrrev_i16_sdwa v4, v254, sext(v4) dst_sel:DWORD dst_unused:UNUSED_PAD src0_sel:DWORD src1_sel:BYTE_0
	v_lshlrev_b32_e32 v6, 1, v5
	v_lshrrev_b32_e32 v8, 2, v5
	v_and_b32_e32 v7, 3, v7
	v_and_b32_e32 v3, 32, v3
	v_bfe_i32 v4, v4, 0, 16
	v_and_b32_e32 v6, 24, v6
	v_and_b32_e32 v8, 4, v8
	v_and_or_b32 v7, v5, s86, v7
	v_or3_b32 v6, v7, v8, v6
	v_add_lshl_u32 v3, v3, v4, 1
	v_add_u32_e32 v2, 0x2000, v2
	v_lshl_add_u32 v154, v5, 11, v3
	v_lshl_add_u32 v160, v6, 11, v3
	v_ashrrev_i32_e32 v3, 31, v2
	v_lshrrev_b32_e32 v3, 22, v3
	v_add_u32_e32 v3, v2, v3
	v_ashrrev_i32_e32 v3, 10, v3
	v_mul_i32_i24_e32 v4, 0x400, v3
	v_sub_u32_e32 v2, v2, v4
	v_lshrrev_b32_e32 v4, 4, v2
	v_bitop3_b32 v2, v4, v2, 32 bitop3:0x6c
	v_ashrrev_i32_e32 v5, 31, v2
	v_lshrrev_b32_e32 v5, 26, v5
	v_lshlrev_b32_e32 v4, 3, v3
	v_add_u32_e32 v5, v2, v5
	v_and_b32_e32 v4, -16, v4
	v_ashrrev_i32_e32 v6, 6, v5
	v_and_b32_e32 v5, 0xc0, v5
	v_add_u32_e32 v4, v6, v4
	v_sub_u32_e32 v2, v2, v5
	v_lshlrev_b32_e32 v3, 5, v3
	v_ashrrev_i16_sdwa v2, v254, sext(v2) dst_sel:DWORD dst_unused:UNUSED_PAD src0_sel:DWORD src1_sel:BYTE_0
	v_lshlrev_b32_e32 v5, 1, v4
	v_lshrrev_b32_e32 v7, 2, v4
	v_and_b32_e32 v6, 3, v6
	v_and_b32_e32 v3, 32, v3
	v_bfe_i32 v2, v2, 0, 16
	v_and_b32_e32 v5, 24, v5
	v_and_b32_e32 v7, 4, v7
	v_and_or_b32 v6, v4, s86, v6
	v_or3_b32 v5, v6, v7, v5
	v_add_lshl_u32 v2, v3, v2, 1
	v_lshl_add_u32 v156, v4, 11, v2
	v_lshl_add_u32 v158, v5, 11, v2
	v_and_b32_e32 v2, 15, v0
	v_or_b32_e32 v3, s69, v2
	v_and_b32_e32 v4, 48, v0
	v_lshlrev_b32_e32 v0, 2, v0
	v_lshlrev_b32_e32 v5, 6, v3
	v_lshlrev_b32_e32 v3, 2, v3
	v_lshl_or_b32 v2, v2, 6, v4
	v_and_b32_e32 v0, 32, v0
	v_and_or_b32 v5, v5, s89, v4
	v_and_b32_e32 v3, 32, v3
	v_bitop3_b32 v179, v2, s72, v0 bitop3:0xde
	v_mov_b32_e32 v2, 0
	v_bitop3_b32 v178, v5, s70, v3 bitop3:0xde
	s_mov_b32 s4, s79
	s_mov_b32 s5, s78
	s_mov_b32 s80, s31
	v_mov_b32_e32 v3, v2
	v_mov_b64_e32 v[4:5], 0
	v_mov_b64_e32 v[6:7], 0
	v_mov_b64_e32 v[8:9], 0
	v_mov_b64_e32 v[10:11], 0
	v_mov_b64_e32 v[12:13], 0
	v_mov_b64_e32 v[14:15], 0
	v_mov_b64_e32 v[16:17], 0
	v_mov_b64_e32 v[18:19], 0
	v_mov_b64_e32 v[20:21], 0
	v_mov_b64_e32 v[22:23], 0
	v_mov_b64_e32 v[24:25], 0
	v_mov_b64_e32 v[26:27], 0
	v_mov_b64_e32 v[28:29], 0
	v_mov_b64_e32 v[30:31], 0
	v_mov_b64_e32 v[32:33], 0
	v_mov_b64_e32 v[34:35], 0
	v_mov_b64_e32 v[36:37], 0
	v_mov_b64_e32 v[38:39], 0
	v_mov_b64_e32 v[40:41], 0
	v_mov_b64_e32 v[42:43], 0
	v_mov_b64_e32 v[44:45], 0
	v_mov_b64_e32 v[46:47], 0
	v_mov_b64_e32 v[48:49], 0
	v_mov_b64_e32 v[50:51], 0
	v_mov_b64_e32 v[52:53], 0
	v_mov_b64_e32 v[54:55], 0
	v_mov_b64_e32 v[56:57], 0
	v_mov_b64_e32 v[58:59], 0
	v_mov_b64_e32 v[60:61], 0
	v_mov_b64_e32 v[62:63], 0
	v_mov_b64_e32 v[64:65], 0
	v_mov_b64_e32 v[66:67], 0
	v_mov_b64_e32 v[68:69], 0
	v_mov_b64_e32 v[70:71], 0
	v_mov_b64_e32 v[72:73], 0
	v_mov_b64_e32 v[74:75], 0
	v_mov_b64_e32 v[76:77], 0
	v_mov_b64_e32 v[78:79], 0
	v_mov_b64_e32 v[80:81], 0
	v_mov_b64_e32 v[82:83], 0
	v_mov_b64_e32 v[84:85], 0
	v_mov_b64_e32 v[86:87], 0
	v_mov_b64_e32 v[88:89], 0
	v_mov_b64_e32 v[90:91], 0
	v_mov_b64_e32 v[92:93], 0
	v_mov_b64_e32 v[94:95], 0
	v_mov_b64_e32 v[96:97], 0
	v_mov_b64_e32 v[98:99], 0
	v_mov_b64_e32 v[100:101], 0
	v_mov_b64_e32 v[102:103], 0
	v_mov_b64_e32 v[104:105], 0
	v_mov_b64_e32 v[106:107], 0
	v_mov_b64_e32 v[108:109], 0
	v_mov_b64_e32 v[110:111], 0
	v_mov_b64_e32 v[112:113], 0
	v_mov_b64_e32 v[114:115], 0
	v_mov_b64_e32 v[116:117], 0
	v_mov_b64_e32 v[118:119], 0
	v_mov_b64_e32 v[120:121], 0
	v_mov_b64_e32 v[122:123], 0
	v_mov_b64_e32 v[124:125], 0
	v_mov_b64_e32 v[126:127], 0
	v_mov_b64_e32 v[128:129], 0
	s_mov_b64 s[56:57], s[60:61]
	s_andn2_b64 vcc, exec, s[6:7]
	s_mov_b64 s[62:63], s[58:59]
	s_cbranch_vccz .LBB0_1524

; #define PG8_STAGE(bufoff, gbase, voff) do { _Pragma("unroll") for (int _i = 0; _i < 2; ++_i) \
;         __builtin_amdgcn_global_load_lds((const unsigned*)((const char*)(gbase) + (voff)[_i]), (LAS unsigned*)(lds + (bufoff) + ldsw + _i * 8192), 16, 0, 0); } while (0)
; #define PG8_WAIT_V(n) asm volatile("s_waitcnt vmcnt(" #n ")" ::: "memory")
; #define PG8_BAR __builtin_amdgcn_s_barrier()
; template <class Epi, class Sched, bool ALIGN_EPI>
; __device__ __forceinline__ void gemm_phase(LAS unsigned char* lds, const bf16_t* Ab, const bf16_t* Bb, int lda, int ldb, int K, const Sched& S, Epi& E) {
;     ...
;     f32x4 acc[2][2][4][2];
; #pragma unroll
;     for (int a = 0; a < 2; ++a)
; #pragma unroll
;         for (int b = 0; b < 2; ++b)
; #pragma unroll
;             for (int m = 0; m < 4; ++m)
; #pragma unroll
;                 for (int n = 0; n < 2; ++n) acc[a][b][m][n] = (f32x4){0.f, 0.f, 0.f, 0.f};
;     bf16x8 At[4][2], B0[2][2], B1[2][2];
;     const char* cA = (const char*)(Ab + cur.a_off); const char* cB = (const char*)(Bb + cur.b_off);
;     PG8_STAGE(PG8_SB(0, 0), cB, voffB); PG8_STAGE(PG8_SB(0, 1), cB + hstepB, voffB); PG8_STAGE(PG8_SA(0, 0), cA, voffA); PG8_STAGE(PG8_SA(0, 1), cA + hstepA, voffA);
;     if (wr == 1) PG8_BAR;
;     PG8_WAIT_V(2); PG8_BAR;
;     PG8_STAGE(PG8_SB(1, 0), cB + kstep, voffB); PG8_STAGE(PG8_SA(1, 0), cA + kstep, voffA); PG8_STAGE(PG8_SB(1, 1), cB + hstepB + kstep, voffB);
;     PG8_WAIT_V(6); PG8_BAR;
.LBB0_1635:
	s_add_u32 s12, s52, 0xe800000
	s_addc_u32 s13, s53, 0
	s_lshl_b32 s6, s6, 5
	s_and_b32 s6, s6, 0x60
	s_add_i32 m0, s44, 0x18000
	v_lshl_add_u64 v[10:11], v[10:11], 0, s[26:27]
	s_lshl_b32 s47, s7, 6
	s_lshl_b32 s66, s7, 13
	s_lshl_b32 s67, s6, 7
	s_waitcnt vmcnt(2)
	s_barrier
	global_load_lds_dwordx4 v[10:11], off
	v_lshl_add_u64 v[8:9], v[8:9], 0, s[26:27]
	s_add_i32 m0, s44, 0x1a000
	s_add_i32 s68, s44, 0x8000
	s_add_i32 s69, s44, 0xa000
	global_load_lds_dwordx4 v[8:9], off
	v_lshl_add_u64 v[2:3], v[2:3], 0, s[26:27]
	s_mov_b32 m0, s68
	s_add_u32 s8, s60, 0x40080
	global_load_lds_dwordx4 v[2:3], off
	v_lshl_add_u64 v[2:3], v[6:7], 0, s[26:27]
	s_mov_b32 m0, s69
	s_addc_u32 s9, s61, 0
	global_load_lds_dwordx4 v[2:3], off
	s_add_i32 m0, s44, 0x1c000
	v_lshl_add_u64 v[2:3], s[8:9], 0, v[0:1]
	global_load_lds_dwordx4 v[2:3], off
	v_lshl_add_u64 v[2:3], s[8:9], 0, v[132:133]
	s_add_i32 m0, s44, 0x1e000
	v_and_b32_e32 v5, 48, v98
	global_load_lds_dwordx4 v[2:3], off
	v_lshlrev_b32_e32 v12, 6, v98
	s_cmpk_lt_u32 s62, 0x100
	v_and_or_b32 v5, v12, s89, v5
	v_lshlrev_b32_e32 v12, 2, v98
	s_waitcnt vmcnt(6)
	s_cselect_b64 s[14:15], -1, 0
	s_lshl_b32 s7, s7, 8
	v_and_b32_e32 v12, 32, v12
	s_add_i32 s70, s7, 0
	v_mov_b32_e32 v2, 0
	v_bitop3_b32 v140, v5, s66, v12 bitop3:0xde
	v_bitop3_b32 v141, s67, v5, v12 bitop3:0xf6
	s_add_i32 s70, s70, 0x22100
	s_mov_b32 s73, 0
	s_lshl_b32 s18, s6, 1
	v_mov_b32_e32 v134, v0
	v_mov_b32_e32 v0, v4
	v_mov_b32_e32 v3, v2
	v_mov_b64_e32 v[4:5], 0
	v_mov_b64_e32 v[6:7], 0
	v_mov_b64_e32 v[8:9], 0
	v_mov_b64_e32 v[10:11], 0
	v_mov_b64_e32 v[12:13], 0
	s_waitcnt vmcnt(0)
	v_mov_b64_e32 v[14:15], 0
	v_mov_b64_e32 v[16:17], 0
	v_mov_b64_e32 v[18:19], 0
	v_mov_b64_e32 v[20:21], 0
	v_mov_b64_e32 v[22:23], 0
	v_mov_b64_e32 v[24:25], 0
	v_mov_b64_e32 v[26:27], 0
	v_mov_b64_e32 v[28:29], 0
	v_mov_b64_e32 v[30:31], 0
	v_mov_b64_e32 v[32:33], 0
	v_mov_b64_e32 v[34:35], 0
	v_mov_b64_e32 v[36:37], 0
	v_mov_b64_e32 v[38:39], 0
	v_mov_b64_e32 v[40:41], 0
	v_mov_b64_e32 v[42:43], 0
	v_mov_b64_e32 v[44:45], 0
	v_mov_b64_e32 v[46:47], 0
	v_mov_b64_e32 v[48:49], 0
	v_mov_b64_e32 v[50:51], 0
	v_mov_b64_e32 v[52:53], 0
	v_mov_b64_e32 v[54:55], 0
	v_mov_b64_e32 v[56:57], 0
	v_mov_b64_e32 v[58:59], 0
	v_mov_b64_e32 v[60:61], 0
	v_mov_b64_e32 v[62:63], 0
	v_mov_b64_e32 v[64:65], 0
	v_mov_b64_e32 v[66:67], 0
	v_mov_b64_e32 v[68:69], 0
	v_mov_b64_e32 v[70:71], 0
	v_mov_b64_e32 v[72:73], 0
	v_mov_b64_e32 v[74:75], 0
	v_mov_b64_e32 v[76:77], 0
	v_mov_b64_e32 v[78:79], 0
	v_mov_b64_e32 v[80:81], 0
	v_mov_b64_e32 v[82:83], 0
	v_mov_b64_e32 v[84:85], 0
	v_mov_b64_e32 v[86:87], 0
	v_mov_b64_e32 v[88:89], 0
	v_mov_b64_e32 v[90:91], 0
	v_mov_b64_e32 v[92:93], 0
	v_mov_b64_e32 v[94:95], 0
	v_mov_b64_e32 v[96:97], 0
	v_mov_b64_e32 v[98:99], 0
	v_mov_b64_e32 v[100:101], 0
	v_mov_b64_e32 v[102:103], 0
	v_mov_b64_e32 v[104:105], 0
	v_mov_b64_e32 v[106:107], 0
	v_mov_b64_e32 v[108:109], 0
	v_mov_b64_e32 v[110:111], 0
	v_mov_b64_e32 v[112:113], 0
	v_mov_b64_e32 v[114:115], 0
	v_mov_b64_e32 v[116:117], 0
	v_mov_b64_e32 v[118:119], 0
	v_mov_b64_e32 v[120:121], 0
	v_mov_b64_e32 v[122:123], 0
	v_mov_b64_e32 v[124:125], 0
	v_mov_b64_e32 v[126:127], 0
	v_mov_b64_e32 v[128:129], 0
	s_barrier
	s_branch .LBB0_1637
; template <class Epi, class Sched, bool ALIGN_EPI>
; __device__ __forceinline__ void gemm_phase(LAS unsigned char* lds, const bf16_t* Ab, const bf16_t* Bb, int lda, int ldb, int K, const Sched& S, Epi& E) {
;     ...
; #pragma unroll
;         for (int a = 0; a < 2; ++a)
; #pragma unroll
;             for (int b = 0; b < 2; ++b)
; #pragma unroll
;                 for (int m = 0; m < 4; ++m)
; #pragma unroll
;                     for (int n = 0; n < 2; ++n) acc[a][b][m][n] = (f32x4){0.f, 0.f, 0.f, 0.f};
;         cur = nxt; cA = nA; cB = nB; ++ui;
;         { int t3 = threadIdx.x; asm volatile("" : "+v"(t3)); PG8_LANEOFFS(t3); }
.LBB0_1636:
	v_bfe_i32 v4, v2, 27, 1
	v_lshlrev_b32_e32 v3, 4, v2
	v_lshrrev_b32_e32 v4, 22, v4
	v_add_u32_e32 v4, v3, v4
	v_and_b32_e32 v4, 0xfffffc00, v4
	v_sub_u32_e32 v4, v3, v4
	v_ashrrev_i32_e32 v0, 31, v2
	v_lshrrev_b32_e32 v5, 4, v4
	v_lshrrev_b32_e32 v0, 26, v0
	v_bitop3_b32 v4, v5, v4, 32 bitop3:0x6c
	v_add_u32_e32 v0, v2, v0
	v_ashrrev_i32_e32 v6, 31, v4
	v_ashrrev_i32_e32 v0, 6, v0
	v_lshrrev_b32_e32 v6, 26, v6
	v_lshlrev_b32_e32 v5, 3, v0
	v_add_u32_e32 v6, v4, v6
	v_and_b32_e32 v5, -16, v5
	v_ashrrev_i32_e32 v7, 6, v6
	v_and_b32_e32 v6, 0xc0, v6
	v_add_u32_e32 v5, v7, v5
	v_sub_u32_e32 v4, v4, v6
	v_lshlrev_b32_e32 v0, 5, v0
	v_ashrrev_i16_sdwa v4, v254, sext(v4) dst_sel:DWORD dst_unused:UNUSED_PAD src0_sel:DWORD src1_sel:BYTE_0
	v_lshlrev_b32_e32 v6, 1, v5
	v_lshrrev_b32_e32 v8, 2, v5
	v_and_b32_e32 v7, 3, v7
	v_and_b32_e32 v0, 32, v0
	v_bfe_i32 v4, v4, 0, 16
	v_and_b32_e32 v6, 24, v6
	v_and_b32_e32 v8, 4, v8
	v_and_or_b32 v7, v5, s86, v7
	v_or3_b32 v6, v7, v8, v6
	v_add_lshl_u32 v4, v0, v4, 1
	v_add_u32_e32 v3, 0x2000, v3
	v_lshl_add_u32 v0, v5, 11, v4
	v_lshl_add_u32 v134, v6, 11, v4
	v_ashrrev_i32_e32 v4, 31, v3
	v_lshrrev_b32_e32 v4, 22, v4
	v_add_u32_e32 v4, v3, v4
	v_ashrrev_i32_e32 v4, 10, v4
	v_mul_i32_i24_e32 v5, 0x400, v4
	v_sub_u32_e32 v3, v3, v5
	v_lshrrev_b32_e32 v5, 4, v3
	v_bitop3_b32 v3, v5, v3, 32 bitop3:0x6c
	v_ashrrev_i32_e32 v6, 31, v3
	v_lshrrev_b32_e32 v6, 26, v6
	v_lshlrev_b32_e32 v5, 3, v4
	v_add_u32_e32 v6, v3, v6
	v_and_b32_e32 v5, -16, v5
	v_ashrrev_i32_e32 v7, 6, v6
	v_and_b32_e32 v6, 0xc0, v6
	v_add_u32_e32 v5, v7, v5
	v_sub_u32_e32 v3, v3, v6
	v_lshlrev_b32_e32 v4, 5, v4
	v_ashrrev_i16_sdwa v3, v254, sext(v3) dst_sel:DWORD dst_unused:UNUSED_PAD src0_sel:DWORD src1_sel:BYTE_0
	v_lshlrev_b32_e32 v6, 1, v5
	v_lshrrev_b32_e32 v8, 2, v5
	v_and_b32_e32 v7, 3, v7
	v_and_b32_e32 v4, 32, v4
	v_bfe_i32 v3, v3, 0, 16
	v_and_b32_e32 v6, 24, v6
	v_and_b32_e32 v8, 4, v8
	v_and_or_b32 v7, v5, s86, v7
	v_or3_b32 v6, v7, v8, v6
	v_add_lshl_u32 v3, v4, v3, 1
	v_lshl_add_u32 v130, v5, 11, v3
	v_lshl_add_u32 v132, v6, 11, v3
	v_and_b32_e32 v3, 15, v2
	v_or_b32_e32 v4, s47, v3
	v_and_b32_e32 v5, 48, v2
	v_lshlrev_b32_e32 v2, 2, v2
	v_lshlrev_b32_e32 v6, 6, v4
	v_lshlrev_b32_e32 v4, 2, v4
	v_lshl_or_b32 v3, v3, 6, v5
	v_and_b32_e32 v2, 32, v2
	v_and_or_b32 v6, v6, s89, v5
	v_and_b32_e32 v4, 32, v4
	v_bitop3_b32 v141, v3, s67, v2 bitop3:0xde
	v_mov_b32_e32 v2, 0
	v_bitop3_b32 v140, v6, s66, v4 bitop3:0xde
	s_mov_b32 s4, s72
	s_mov_b32 s5, s71
	s_mov_b32 s73, s74
	v_mov_b32_e32 v3, v2
	v_mov_b64_e32 v[4:5], 0
	v_mov_b64_e32 v[6:7], 0
	v_mov_b64_e32 v[8:9], 0
	v_mov_b64_e32 v[10:11], 0
	v_mov_b64_e32 v[12:13], 0
	v_mov_b64_e32 v[14:15], 0
	v_mov_b64_e32 v[16:17], 0
	v_mov_b64_e32 v[18:19], 0
	v_mov_b64_e32 v[20:21], 0
	v_mov_b64_e32 v[22:23], 0
	v_mov_b64_e32 v[24:25], 0
	v_mov_b64_e32 v[26:27], 0
	v_mov_b64_e32 v[28:29], 0
	v_mov_b64_e32 v[30:31], 0
	v_mov_b64_e32 v[32:33], 0
	v_mov_b64_e32 v[34:35], 0
	v_mov_b64_e32 v[36:37], 0
	v_mov_b64_e32 v[38:39], 0
	v_mov_b64_e32 v[40:41], 0
	v_mov_b64_e32 v[42:43], 0
	v_mov_b64_e32 v[44:45], 0
	v_mov_b64_e32 v[46:47], 0
	v_mov_b64_e32 v[48:49], 0
	v_mov_b64_e32 v[50:51], 0
	v_mov_b64_e32 v[52:53], 0
	v_mov_b64_e32 v[54:55], 0
	v_mov_b64_e32 v[56:57], 0
	v_mov_b64_e32 v[58:59], 0
	v_mov_b64_e32 v[60:61], 0
	v_mov_b64_e32 v[62:63], 0
	v_mov_b64_e32 v[64:65], 0
	v_mov_b64_e32 v[66:67], 0
	v_mov_b64_e32 v[68:69], 0
	v_mov_b64_e32 v[70:71], 0
	v_mov_b64_e32 v[72:73], 0
	v_mov_b64_e32 v[74:75], 0
	v_mov_b64_e32 v[76:77], 0
	v_mov_b64_e32 v[78:79], 0
	v_mov_b64_e32 v[80:81], 0
	v_mov_b64_e32 v[82:83], 0
	v_mov_b64_e32 v[84:85], 0
	v_mov_b64_e32 v[86:87], 0
	v_mov_b64_e32 v[88:89], 0
	v_mov_b64_e32 v[90:91], 0
	v_mov_b64_e32 v[92:93], 0
	v_mov_b64_e32 v[94:95], 0
	v_mov_b64_e32 v[96:97], 0
	v_mov_b64_e32 v[98:99], 0
	v_mov_b64_e32 v[100:101], 0
	v_mov_b64_e32 v[102:103], 0
	v_mov_b64_e32 v[104:105], 0
	v_mov_b64_e32 v[106:107], 0
	v_mov_b64_e32 v[108:109], 0
	v_mov_b64_e32 v[110:111], 0
	v_mov_b64_e32 v[112:113], 0
	v_mov_b64_e32 v[114:115], 0
	v_mov_b64_e32 v[116:117], 0
	v_mov_b64_e32 v[118:119], 0
	v_mov_b64_e32 v[120:121], 0
	v_mov_b64_e32 v[122:123], 0
	v_mov_b64_e32 v[124:125], 0
	v_mov_b64_e32 v[126:127], 0
	v_mov_b64_e32 v[128:129], 0
	s_mov_b64 s[54:55], s[58:59]
	s_andn2_b64 vcc, exec, s[6:7]
	s_mov_b64 s[60:61], s[56:57]
	s_cbranch_vccz .LBB0_1651

; template <class Epi, class Sched, bool ALIGN_EPI>
; __device__ __forceinline__ void gemm_phase(LAS unsigned char* lds, const bf16_t* Ab, const bf16_t* Bb, int lda, int ldb, int K, const Sched& S, Epi& E) {
;     ...
;         const bool has_next = S.next(ui + 1, nxt); nxt.ui = ui + 1;
;         const char* nA = has_next ? (const char*)(Ab + nxt.a_off) : cA; const char* nB = has_next ? (const char*)(Bb + nxt.b_off) : cB;
;         for (int t = 0; t < nt; t += 2) {
;             const bool last = (t == nt - 2);
;             const char* a1 = cA + (unsigned)(t + 1) * kstep;
;             const char* a2 = last ? nA : cA + (unsigned)(t + 2) * kstep; const char* b2 = last ? nB : cB + (unsigned)(t + 2) * kstep;
;             const char* a3 = a2 + kstep; const char* b3 = b2 + kstep;
;     ...
; #pragma unroll
;         for (int a = 0; a < 2; ++a)
; #pragma unroll
;             for (int b = 0; b < 2; ++b)
; #pragma unroll
;                 for (int m = 0; m < 4; ++m)
; #pragma unroll
;                     for (int n = 0; n < 2; ++n) acc[a][b][m][n] = (f32x4){0.f, 0.f, 0.f, 0.f};
.LBB0_1891:
	s_mov_b32 s17, s19
	s_lshl_b64 s[50:51], s[16:17], 1
	s_add_u32 s50, s4, s50
	s_addc_u32 s51, s5, s51
	s_and_b64 s[52:53], s[6:7], exec
	s_mov_b32 s49, s19
	s_cselect_b32 s17, s51, s57
	s_cselect_b32 s18, s50, s56
	s_lshl_b64 s[52:53], s[48:49], 1
	s_add_u32 s52, s21, s52
	s_addc_u32 s53, s22, s53
	s_and_b64 s[58:59], s[6:7], exec
	s_cselect_b32 s25, s53, s55
	s_cselect_b32 s49, s52, s54
	s_add_u32 s74, s54, 0x100
	s_addc_u32 s75, s55, 0
	v_add_u32_e32 v3, s47, v2
	s_add_u32 s54, s56, 0x40080
	v_mov_b32_e32 v2, 0
	v_add_u32_e32 v136, s61, v10
	v_mov_b32_e32 v135, v1
	v_mov_b32_e32 v131, v1
	v_mov_b32_e32 v133, v1
	s_addc_u32 s55, s57, 0
	s_mov_b32 s76, -2
	v_add_u32_e32 v137, 0, v3
	v_mov_b32_e32 v3, v2
	v_mov_b64_e32 v[4:5], 0
	v_mov_b64_e32 v[6:7], 0
	v_mov_b64_e32 v[8:9], 0
	v_mov_b64_e32 v[18:19], 0
	v_mov_b64_e32 v[20:21], 0
	v_mov_b64_e32 v[22:23], 0
	v_mov_b64_e32 v[24:25], 0
	v_mov_b64_e32 v[34:35], 0
	v_mov_b64_e32 v[36:37], 0
	v_mov_b64_e32 v[38:39], 0
	v_mov_b64_e32 v[40:41], 0
	v_mov_b64_e32 v[50:51], 0
	v_mov_b64_e32 v[52:53], 0
	v_mov_b64_e32 v[54:55], 0
	v_mov_b64_e32 v[56:57], 0
	v_mov_b64_e32 v[10:11], 0
	v_mov_b64_e32 v[12:13], 0
	v_mov_b64_e32 v[14:15], 0
	v_mov_b64_e32 v[16:17], 0
	v_mov_b64_e32 v[26:27], 0
	v_mov_b64_e32 v[28:29], 0
	v_mov_b64_e32 v[30:31], 0
	v_mov_b64_e32 v[32:33], 0
	v_mov_b64_e32 v[42:43], 0
	v_mov_b64_e32 v[44:45], 0
	v_mov_b64_e32 v[46:47], 0
	v_mov_b64_e32 v[48:49], 0
	v_mov_b64_e32 v[58:59], 0
	v_mov_b64_e32 v[60:61], 0
	v_mov_b64_e32 v[62:63], 0
	v_mov_b64_e32 v[64:65], 0
	v_mov_b64_e32 v[66:67], 0
	v_mov_b64_e32 v[68:69], 0
	v_mov_b64_e32 v[70:71], 0
	v_mov_b64_e32 v[72:73], 0
	v_mov_b64_e32 v[82:83], 0
	v_mov_b64_e32 v[84:85], 0
	v_mov_b64_e32 v[86:87], 0
	v_mov_b64_e32 v[88:89], 0
	v_mov_b64_e32 v[98:99], 0
	v_mov_b64_e32 v[100:101], 0
	v_mov_b64_e32 v[102:103], 0
	v_mov_b64_e32 v[104:105], 0
	v_mov_b64_e32 v[114:115], 0
	v_mov_b64_e32 v[116:117], 0
	v_mov_b64_e32 v[118:119], 0
	v_mov_b64_e32 v[120:121], 0
	v_mov_b64_e32 v[74:75], 0
	v_mov_b64_e32 v[76:77], 0
	v_mov_b64_e32 v[78:79], 0
	v_mov_b64_e32 v[80:81], 0
	v_mov_b64_e32 v[90:91], 0
	v_mov_b64_e32 v[92:93], 0
	v_mov_b64_e32 v[94:95], 0
	v_mov_b64_e32 v[96:97], 0
	v_mov_b64_e32 v[106:107], 0
	v_mov_b64_e32 v[108:109], 0
	v_mov_b64_e32 v[110:111], 0
	v_mov_b64_e32 v[112:113], 0
	v_mov_b64_e32 v[122:123], 0
	v_mov_b64_e32 v[124:125], 0
	v_mov_b64_e32 v[126:127], 0
	v_mov_b64_e32 v[128:129], 0

; #define PG8_STAGE(bufoff, gbase, voff) do { _Pragma("unroll") for (int _i = 0; _i < 2; ++_i) \
;         __builtin_amdgcn_global_load_lds((const unsigned*)((const char*)(gbase) + (voff)[_i]), (LAS unsigned*)(lds + (bufoff) + ldsw + _i * 8192), 16, 0, 0); } while (0)
; #define PG8_WAIT_V(n) asm volatile("s_waitcnt vmcnt(" #n ")" ::: "memory")
; #define PG8_BAR __builtin_amdgcn_s_barrier()
; template <class Epi, class Sched, bool ALIGN_EPI>
; __device__ __forceinline__ void gemm_phase(LAS unsigned char* lds, const bf16_t* Ab, const bf16_t* Bb, int lda, int ldb, int K, const Sched& S, Epi& E) {
;     ...
;     f32x4 acc[2][2][4][2];
; #pragma unroll
;     for (int a = 0; a < 2; ++a)
; #pragma unroll
;         for (int b = 0; b < 2; ++b)
; #pragma unroll
;             for (int m = 0; m < 4; ++m)
; #pragma unroll
;                 for (int n = 0; n < 2; ++n) acc[a][b][m][n] = (f32x4){0.f, 0.f, 0.f, 0.f};
;     bf16x8 At[4][2], B0[2][2], B1[2][2];
;     const char* cA = (const char*)(Ab + cur.a_off); const char* cB = (const char*)(Bb + cur.b_off);
;     PG8_STAGE(PG8_SB(0, 0), cB, voffB); PG8_STAGE(PG8_SB(0, 1), cB + hstepB, voffB); PG8_STAGE(PG8_SA(0, 0), cA, voffA); PG8_STAGE(PG8_SA(0, 1), cA + hstepA, voffA);
;     if (wr == 1) PG8_BAR;
;     PG8_WAIT_V(2); PG8_BAR;
;     PG8_STAGE(PG8_SB(1, 0), cB + kstep, voffB); PG8_STAGE(PG8_SA(1, 0), cA + kstep, voffA); PG8_STAGE(PG8_SB(1, 1), cB + hstepB + kstep, voffB);
;     PG8_WAIT_V(6); PG8_BAR;
.LBB0_1997:
	s_add_u32 s12, s50, 0xe800000
	s_addc_u32 s13, s51, 0
	s_lshl_b32 s6, s6, 5
	s_and_b32 s6, s6, 0x60
	s_add_i32 m0, s44, 0x18000
	v_lshl_add_u64 v[10:11], v[10:11], 0, s[26:27]
	s_lshl_b32 s64, s7, 6
	s_lshl_b32 s65, s7, 13
	s_lshl_b32 s66, s6, 7
	s_waitcnt vmcnt(2)
	s_barrier
	global_load_lds_dwordx4 v[10:11], off
	v_lshl_add_u64 v[8:9], v[8:9], 0, s[26:27]
	s_add_i32 m0, s44, 0x1a000
	s_add_i32 s67, s44, 0x8000
	s_add_i32 s68, s44, 0xa000
	global_load_lds_dwordx4 v[8:9], off
	v_lshl_add_u64 v[2:3], v[2:3], 0, s[26:27]
	s_mov_b32 m0, s67
	s_add_u32 s8, s58, 0x40080
	global_load_lds_dwordx4 v[2:3], off
	v_lshl_add_u64 v[2:3], v[6:7], 0, s[26:27]
	s_mov_b32 m0, s68
	s_addc_u32 s9, s59, 0
	global_load_lds_dwordx4 v[2:3], off
	s_add_i32 m0, s44, 0x1c000
	v_lshl_add_u64 v[2:3], s[8:9], 0, v[0:1]
	global_load_lds_dwordx4 v[2:3], off
	v_lshl_add_u64 v[2:3], s[8:9], 0, v[132:133]
	s_add_i32 m0, s44, 0x1e000
	v_and_b32_e32 v5, 48, v98
	global_load_lds_dwordx4 v[2:3], off
	v_lshlrev_b32_e32 v12, 6, v98
	s_cmpk_lt_u32 s25, 0x100
	v_and_or_b32 v5, v12, s89, v5
	v_lshlrev_b32_e32 v12, 2, v98
	s_waitcnt vmcnt(6)
	s_cselect_b64 s[14:15], -1, 0
	s_lshl_b32 s7, s7, 8
	v_and_b32_e32 v12, 32, v12
	s_add_i32 s69, s7, 0
	v_mov_b32_e32 v2, 0
	v_bitop3_b32 v140, v5, s65, v12 bitop3:0xde
	v_bitop3_b32 v141, s66, v5, v12 bitop3:0xf6
	s_add_i32 s69, s69, 0x22100
	s_mov_b32 s72, 0
	s_lshl_b32 s18, s6, 1
	v_mov_b32_e32 v134, v0
	v_mov_b32_e32 v0, v4
	v_mov_b32_e32 v3, v2
	v_mov_b64_e32 v[4:5], 0
	v_mov_b64_e32 v[6:7], 0
	v_mov_b64_e32 v[8:9], 0
	v_mov_b64_e32 v[10:11], 0
	v_mov_b64_e32 v[12:13], 0
	s_waitcnt vmcnt(0)
	v_mov_b64_e32 v[14:15], 0
	v_mov_b64_e32 v[16:17], 0
	v_mov_b64_e32 v[18:19], 0
	v_mov_b64_e32 v[20:21], 0
	v_mov_b64_e32 v[22:23], 0
	v_mov_b64_e32 v[24:25], 0
	v_mov_b64_e32 v[26:27], 0
	v_mov_b64_e32 v[28:29], 0
	v_mov_b64_e32 v[30:31], 0
	v_mov_b64_e32 v[32:33], 0
	v_mov_b64_e32 v[34:35], 0
	v_mov_b64_e32 v[36:37], 0
	v_mov_b64_e32 v[38:39], 0
	v_mov_b64_e32 v[40:41], 0
	v_mov_b64_e32 v[42:43], 0
	v_mov_b64_e32 v[44:45], 0
	v_mov_b64_e32 v[46:47], 0
	v_mov_b64_e32 v[48:49], 0
	v_mov_b64_e32 v[50:51], 0
	v_mov_b64_e32 v[52:53], 0
	v_mov_b64_e32 v[54:55], 0
	v_mov_b64_e32 v[56:57], 0
	v_mov_b64_e32 v[58:59], 0
	v_mov_b64_e32 v[60:61], 0
	v_mov_b64_e32 v[62:63], 0
	v_mov_b64_e32 v[64:65], 0
	v_mov_b64_e32 v[66:67], 0
	v_mov_b64_e32 v[68:69], 0
	v_mov_b64_e32 v[70:71], 0
	v_mov_b64_e32 v[72:73], 0
	v_mov_b64_e32 v[74:75], 0
	v_mov_b64_e32 v[76:77], 0
	v_mov_b64_e32 v[78:79], 0
	v_mov_b64_e32 v[80:81], 0
	v_mov_b64_e32 v[82:83], 0
	v_mov_b64_e32 v[84:85], 0
	v_mov_b64_e32 v[86:87], 0
	v_mov_b64_e32 v[88:89], 0
	v_mov_b64_e32 v[90:91], 0
	v_mov_b64_e32 v[92:93], 0
	v_mov_b64_e32 v[94:95], 0
	v_mov_b64_e32 v[96:97], 0
	v_mov_b64_e32 v[98:99], 0
	v_mov_b64_e32 v[100:101], 0
	v_mov_b64_e32 v[102:103], 0
	v_mov_b64_e32 v[104:105], 0
	v_mov_b64_e32 v[106:107], 0
	v_mov_b64_e32 v[108:109], 0
	v_mov_b64_e32 v[110:111], 0
	v_mov_b64_e32 v[112:113], 0
	v_mov_b64_e32 v[114:115], 0
	v_mov_b64_e32 v[116:117], 0
	v_mov_b64_e32 v[118:119], 0
	v_mov_b64_e32 v[120:121], 0
	v_mov_b64_e32 v[122:123], 0
	v_mov_b64_e32 v[124:125], 0
	v_mov_b64_e32 v[126:127], 0
	v_mov_b64_e32 v[128:129], 0
	s_barrier
	s_branch .LBB0_1999
; template <class Epi, class Sched, bool ALIGN_EPI>
; __device__ __forceinline__ void gemm_phase(LAS unsigned char* lds, const bf16_t* Ab, const bf16_t* Bb, int lda, int ldb, int K, const Sched& S, Epi& E) {
;     ...
; #pragma unroll
;         for (int a = 0; a < 2; ++a)
; #pragma unroll
;             for (int b = 0; b < 2; ++b)
; #pragma unroll
;                 for (int m = 0; m < 4; ++m)
; #pragma unroll
;                     for (int n = 0; n < 2; ++n) acc[a][b][m][n] = (f32x4){0.f, 0.f, 0.f, 0.f};
;         cur = nxt; cA = nA; cB = nB; ++ui;
;         { int t3 = threadIdx.x; asm volatile("" : "+v"(t3)); PG8_LANEOFFS(t3); }
.LBB0_1998:
	v_bfe_i32 v4, v2, 27, 1
	v_lshlrev_b32_e32 v3, 4, v2
	v_lshrrev_b32_e32 v4, 22, v4
	v_add_u32_e32 v4, v3, v4
	v_and_b32_e32 v4, 0xfffffc00, v4
	v_sub_u32_e32 v4, v3, v4
	v_ashrrev_i32_e32 v0, 31, v2
	v_lshrrev_b32_e32 v5, 4, v4
	v_lshrrev_b32_e32 v0, 26, v0
	v_bitop3_b32 v4, v5, v4, 32 bitop3:0x6c
	v_add_u32_e32 v0, v2, v0
	v_ashrrev_i32_e32 v6, 31, v4
	v_ashrrev_i32_e32 v0, 6, v0
	v_lshrrev_b32_e32 v6, 26, v6
	v_lshlrev_b32_e32 v5, 3, v0
	v_add_u32_e32 v6, v4, v6
	v_and_b32_e32 v5, -16, v5
	v_ashrrev_i32_e32 v7, 6, v6
	v_and_b32_e32 v6, 0xc0, v6
	v_add_u32_e32 v5, v7, v5
	v_sub_u32_e32 v4, v4, v6
	v_lshlrev_b32_e32 v0, 5, v0
	v_ashrrev_i16_sdwa v4, v254, sext(v4) dst_sel:DWORD dst_unused:UNUSED_PAD src0_sel:DWORD src1_sel:BYTE_0
	v_lshlrev_b32_e32 v6, 1, v5
	v_lshrrev_b32_e32 v8, 2, v5
	v_and_b32_e32 v7, 3, v7
	v_and_b32_e32 v0, 32, v0
	v_bfe_i32 v4, v4, 0, 16
	v_and_b32_e32 v6, 24, v6
	v_and_b32_e32 v8, 4, v8
	v_and_or_b32 v7, v5, s86, v7
	v_or3_b32 v6, v7, v8, v6
	v_add_lshl_u32 v4, v0, v4, 1
	v_add_u32_e32 v3, 0x2000, v3
	v_lshl_add_u32 v0, v5, 11, v4
	v_lshl_add_u32 v134, v6, 11, v4
	v_ashrrev_i32_e32 v4, 31, v3
	v_lshrrev_b32_e32 v4, 22, v4
	v_add_u32_e32 v4, v3, v4
	v_ashrrev_i32_e32 v4, 10, v4
	v_mul_i32_i24_e32 v5, 0x400, v4
	v_sub_u32_e32 v3, v3, v5
	v_lshrrev_b32_e32 v5, 4, v3
	v_bitop3_b32 v3, v5, v3, 32 bitop3:0x6c
	v_ashrrev_i32_e32 v6, 31, v3
	v_lshrrev_b32_e32 v6, 26, v6
	v_lshlrev_b32_e32 v5, 3, v4
	v_add_u32_e32 v6, v3, v6
	v_and_b32_e32 v5, -16, v5
	v_ashrrev_i32_e32 v7, 6, v6
	v_and_b32_e32 v6, 0xc0, v6
	v_add_u32_e32 v5, v7, v5
	v_sub_u32_e32 v3, v3, v6
	v_lshlrev_b32_e32 v4, 5, v4
	v_ashrrev_i16_sdwa v3, v254, sext(v3) dst_sel:DWORD dst_unused:UNUSED_PAD src0_sel:DWORD src1_sel:BYTE_0
	v_lshlrev_b32_e32 v6, 1, v5
	v_lshrrev_b32_e32 v8, 2, v5
	v_and_b32_e32 v7, 3, v7
	v_and_b32_e32 v4, 32, v4
	v_bfe_i32 v3, v3, 0, 16
	v_and_b32_e32 v6, 24, v6
	v_and_b32_e32 v8, 4, v8
	v_and_or_b32 v7, v5, s86, v7
	v_or3_b32 v6, v7, v8, v6
	v_add_lshl_u32 v3, v4, v3, 1
	v_lshl_add_u32 v130, v5, 11, v3
	v_lshl_add_u32 v132, v6, 11, v3
	v_and_b32_e32 v3, 15, v2
	v_or_b32_e32 v4, s64, v3
	v_and_b32_e32 v5, 48, v2
	v_lshlrev_b32_e32 v2, 2, v2
	v_lshlrev_b32_e32 v6, 6, v4
	v_lshlrev_b32_e32 v4, 2, v4
	v_lshl_or_b32 v3, v3, 6, v5
	v_and_b32_e32 v2, 32, v2
	v_and_or_b32 v6, v6, s89, v5
	v_and_b32_e32 v4, 32, v4
	v_bitop3_b32 v141, v3, s66, v2 bitop3:0xde
	v_mov_b32_e32 v2, 0
	v_bitop3_b32 v140, v6, s65, v4 bitop3:0xde
	s_mov_b32 s4, s71
	s_mov_b32 s5, s70
	s_mov_b32 s72, s73
	v_mov_b32_e32 v3, v2
	v_mov_b64_e32 v[4:5], 0
	v_mov_b64_e32 v[6:7], 0
	v_mov_b64_e32 v[8:9], 0
	v_mov_b64_e32 v[10:11], 0
	v_mov_b64_e32 v[12:13], 0
	v_mov_b64_e32 v[14:15], 0
	v_mov_b64_e32 v[16:17], 0
	v_mov_b64_e32 v[18:19], 0
	v_mov_b64_e32 v[20:21], 0
	v_mov_b64_e32 v[22:23], 0
	v_mov_b64_e32 v[24:25], 0
	v_mov_b64_e32 v[26:27], 0
	v_mov_b64_e32 v[28:29], 0
	v_mov_b64_e32 v[30:31], 0
	v_mov_b64_e32 v[32:33], 0
	v_mov_b64_e32 v[34:35], 0
	v_mov_b64_e32 v[36:37], 0
	v_mov_b64_e32 v[38:39], 0
	v_mov_b64_e32 v[40:41], 0
	v_mov_b64_e32 v[42:43], 0
	v_mov_b64_e32 v[44:45], 0
	v_mov_b64_e32 v[46:47], 0
	v_mov_b64_e32 v[48:49], 0
	v_mov_b64_e32 v[50:51], 0
	v_mov_b64_e32 v[52:53], 0
	v_mov_b64_e32 v[54:55], 0
	v_mov_b64_e32 v[56:57], 0
	v_mov_b64_e32 v[58:59], 0
	v_mov_b64_e32 v[60:61], 0
	v_mov_b64_e32 v[62:63], 0
	v_mov_b64_e32 v[64:65], 0
	v_mov_b64_e32 v[66:67], 0
	v_mov_b64_e32 v[68:69], 0
	v_mov_b64_e32 v[70:71], 0
	v_mov_b64_e32 v[72:73], 0
	v_mov_b64_e32 v[74:75], 0
	v_mov_b64_e32 v[76:77], 0
	v_mov_b64_e32 v[78:79], 0
	v_mov_b64_e32 v[80:81], 0
	v_mov_b64_e32 v[82:83], 0
	v_mov_b64_e32 v[84:85], 0
	v_mov_b64_e32 v[86:87], 0
	v_mov_b64_e32 v[88:89], 0
	v_mov_b64_e32 v[90:91], 0
	v_mov_b64_e32 v[92:93], 0
	v_mov_b64_e32 v[94:95], 0
	v_mov_b64_e32 v[96:97], 0
	v_mov_b64_e32 v[98:99], 0
	v_mov_b64_e32 v[100:101], 0
	v_mov_b64_e32 v[102:103], 0
	v_mov_b64_e32 v[104:105], 0
	v_mov_b64_e32 v[106:107], 0
	v_mov_b64_e32 v[108:109], 0
	v_mov_b64_e32 v[110:111], 0
	v_mov_b64_e32 v[112:113], 0
	v_mov_b64_e32 v[114:115], 0
	v_mov_b64_e32 v[116:117], 0
	v_mov_b64_e32 v[118:119], 0
	v_mov_b64_e32 v[120:121], 0
	v_mov_b64_e32 v[122:123], 0
	v_mov_b64_e32 v[124:125], 0
	v_mov_b64_e32 v[126:127], 0
	v_mov_b64_e32 v[128:129], 0
	s_mov_b64 s[52:53], s[56:57]
	s_andn2_b64 vcc, exec, s[6:7]
	s_mov_b64 s[58:59], s[54:55]
	s_cbranch_vccz .LBB0_2009

; template <class Epi, class Sched, bool ALIGN_EPI>
; __device__ __forceinline__ void gemm_phase(LAS unsigned char* lds, const bf16_t* Ab, const bf16_t* Bb, int lda, int ldb, int K, const Sched& S, Epi& E) {
;     ...
;         const bool has_next = S.next(ui + 1, nxt); nxt.ui = ui + 1;
;         const char* nA = has_next ? (const char*)(Ab + nxt.a_off) : cA; const char* nB = has_next ? (const char*)(Bb + nxt.b_off) : cB;
;         for (int t = 0; t < nt; t += 2) {
;             const bool last = (t == nt - 2);
;             const char* a1 = cA + (unsigned)(t + 1) * kstep;
;             const char* a2 = last ? nA : cA + (unsigned)(t + 2) * kstep; const char* b2 = last ? nB : cB + (unsigned)(t + 2) * kstep;
;             const char* a3 = a2 + kstep; const char* b3 = b2 + kstep;
;     ...
; #pragma unroll
;         for (int a = 0; a < 2; ++a)
; #pragma unroll
;             for (int b = 0; b < 2; ++b)
; #pragma unroll
;                 for (int m = 0; m < 4; ++m)
; #pragma unroll
;                     for (int n = 0; n < 2; ++n) acc[a][b][m][n] = (f32x4){0.f, 0.f, 0.f, 0.f};
.LBB0_2081:
	s_mov_b32 s17, s19
	s_lshl_b64 s[48:49], s[16:17], 1
	s_add_u32 s48, s4, s48
	s_addc_u32 s49, s5, s49
	s_and_b64 s[50:51], s[6:7], exec
	s_mov_b32 s45, s19
	s_cselect_b32 s17, s49, s55
	s_cselect_b32 s18, s48, s54
	s_lshl_b64 s[50:51], s[44:45], 1
	s_add_u32 s50, s21, s50
	s_addc_u32 s51, s22, s51
	s_and_b64 s[56:57], s[6:7], exec
	s_cselect_b32 s25, s51, s53
	s_cselect_b32 s45, s50, s52
	s_add_u32 s74, s52, 0x100
	s_addc_u32 s75, s53, 0
	v_add_u32_e32 v3, s59, v2
	s_add_u32 s52, s54, 0xb0080
	v_mov_b32_e32 v2, 0
	v_add_u32_e32 v136, s61, v10
	v_mov_b32_e32 v133, v1
	v_mov_b32_e32 v131, v1
	v_mov_b32_e32 v135, v1
	s_addc_u32 s53, s55, 0
	s_mov_b32 s76, -2
	v_add_u32_e32 v137, 0, v3
	v_mov_b32_e32 v3, v2
	v_mov_b64_e32 v[4:5], 0
	v_mov_b64_e32 v[6:7], 0
	v_mov_b64_e32 v[8:9], 0
	v_mov_b64_e32 v[18:19], 0
	v_mov_b64_e32 v[20:21], 0
	v_mov_b64_e32 v[22:23], 0
	v_mov_b64_e32 v[24:25], 0
	v_mov_b64_e32 v[34:35], 0
	v_mov_b64_e32 v[36:37], 0
	v_mov_b64_e32 v[38:39], 0
	v_mov_b64_e32 v[40:41], 0
	v_mov_b64_e32 v[50:51], 0
	v_mov_b64_e32 v[52:53], 0
	v_mov_b64_e32 v[54:55], 0
	v_mov_b64_e32 v[56:57], 0
	v_mov_b64_e32 v[10:11], 0
	v_mov_b64_e32 v[12:13], 0
	v_mov_b64_e32 v[14:15], 0
	v_mov_b64_e32 v[16:17], 0
	v_mov_b64_e32 v[26:27], 0
	v_mov_b64_e32 v[28:29], 0
	v_mov_b64_e32 v[30:31], 0
	v_mov_b64_e32 v[32:33], 0
	v_mov_b64_e32 v[42:43], 0
	v_mov_b64_e32 v[44:45], 0
	v_mov_b64_e32 v[46:47], 0
	v_mov_b64_e32 v[48:49], 0
	v_mov_b64_e32 v[58:59], 0
	v_mov_b64_e32 v[60:61], 0
	v_mov_b64_e32 v[62:63], 0
	v_mov_b64_e32 v[64:65], 0
	v_mov_b64_e32 v[66:67], 0
	v_mov_b64_e32 v[68:69], 0
	v_mov_b64_e32 v[70:71], 0
	v_mov_b64_e32 v[72:73], 0
	v_mov_b64_e32 v[82:83], 0
	v_mov_b64_e32 v[84:85], 0
	v_mov_b64_e32 v[86:87], 0
	v_mov_b64_e32 v[88:89], 0
	v_mov_b64_e32 v[98:99], 0
	v_mov_b64_e32 v[100:101], 0
	v_mov_b64_e32 v[102:103], 0
	v_mov_b64_e32 v[104:105], 0
	v_mov_b64_e32 v[114:115], 0
	v_mov_b64_e32 v[116:117], 0
	v_mov_b64_e32 v[118:119], 0
	v_mov_b64_e32 v[120:121], 0
	v_mov_b64_e32 v[74:75], 0
	v_mov_b64_e32 v[76:77], 0
	v_mov_b64_e32 v[78:79], 0
	v_mov_b64_e32 v[80:81], 0
	v_mov_b64_e32 v[90:91], 0
	v_mov_b64_e32 v[92:93], 0
	v_mov_b64_e32 v[94:95], 0
	v_mov_b64_e32 v[96:97], 0
	v_mov_b64_e32 v[106:107], 0
	v_mov_b64_e32 v[108:109], 0
	v_mov_b64_e32 v[110:111], 0
	v_mov_b64_e32 v[112:113], 0
	v_mov_b64_e32 v[122:123], 0
	v_mov_b64_e32 v[124:125], 0
	v_mov_b64_e32 v[126:127], 0
	v_mov_b64_e32 v[128:129], 0
